# residual/norm row-loop stores marked nt (streaming cache policy) so the panel-sync L2 writeback has less dirty data
# speedup vs baseline: 1.0064x; 1.0064x over previous
; __device__ __forceinline__ float bf_lo(unsigned w) { return __uint_as_float(w << 16); }
; __device__ __forceinline__ float bf_hi(unsigned w) { return __uint_as_float(w & 0xffff0000u); }
; __device__ __forceinline__ void ew_phase(const Frame& F, const bf16_t* f, const float* gpost, float alpha, const float* hin, float* hout, const float* gpre, bf16_t* xn, ...
;     ...
;         const int m = prow0 >= 0 ? prow0 + F.wave * 8 + it_ : F.gw + it_ * F.NGW; if (m >= T) break;
;         const u32x2* fr = (const u32x2*)(f + (size_t)m * DM) + F.lane; const f32x4* hr = (const f32x4*)(hin + (size_t)m * DM) + F.lane;
;         f32x4 fv[4], hv[4]; float s = 0.f;
; #pragma unroll
;         for (int j = 0; j < 4; ++j) { const u32x2 w = fr[64 * j]; hv[j] = in24 ? load24(h24 + (size_t)m * (DM * 3), F.lane + 64 * j) : hr[64 * j]; fv[j] = (f32x4){bf_lo(w.x), bf_hi(w.x), bf_lo(w.y), bf_hi(w.y)};
;             s += (fv[j].x * fv[j].x + fv[j].y * fv[j].y) + (fv[j].z * fv[j].z + fv[j].w * fv[j].w); }
;         const float rstd = alpha / sqrtf(wave_sum(s) * (1.f / DM) + RMS_EPS);
.LBB0_209:
	v_readlane_b32 s0, v252, 11
	s_add_i32 s2, s14, s9
	v_readlane_b32 s1, v252, 12
	s_and_b64 s[0:1], s[0:1], exec
	s_cselect_b32 s10, s2, s15
	s_cmpk_gt_i32 s10, 0x3fff
	s_mov_b64 s[0:1], -1
	s_cbranch_scc1 .LBB0_208
	s_ashr_i32 s11, s10, 31
	s_lshl_b64 s[12:13], s[10:11], 11
	s_mul_i32 s0, s10, 0xc00
	s_mul_hi_i32 s1, s10, 0xc00
	s_add_u32 s0, s24, s0
	s_addc_u32 s1, s25, s1
	v_lshl_add_u64 v[70:71], v[34:35], 0, s[12:13]
	v_lshl_add_u64 v[54:55], s[0:1], 0, v[38:39]
	v_lshl_add_u64 v[64:65], s[0:1], 0, v[40:41]
	v_lshl_add_u64 v[162:163], s[0:1], 0, v[44:45]
	v_lshl_add_u64 v[164:165], s[0:1], 0, v[46:47]
	global_load_dwordx2 v[62:63], v[70:71], off
	global_load_dwordx2 v[58:59], v[54:55], off
	global_load_dwordx2 v[60:61], v[54:55], off offset:4
	global_load_dwordx2 v[72:73], v[70:71], off offset:512
	global_load_dwordx2 v[68:69], v[64:65], off
	global_load_dwordx2 v[74:75], v[64:65], off offset:4
	global_load_dwordx2 v[78:79], v[70:71], off offset:1024
	global_load_dwordx2 v[82:83], v[162:163], off
	global_load_dwordx2 v[84:85], v[162:163], off offset:4
	global_load_dwordx2 v[86:87], v[70:71], off offset:1536
	global_load_dwordx2 v[166:167], v[164:165], off
	global_load_dwordx2 v[88:89], v[164:165], off offset:4
	s_mov_b32 s2, 0xff00
	s_waitcnt vmcnt(10)
	v_lshrrev_b32_e32 v59, 8, v59
	s_waitcnt vmcnt(9) lgkmcnt(0)
	v_lshlrev_b32_e32 v0, 24, v61
	v_lshlrev_b32_e32 v57, 16, v60
	v_and_b32_e32 v59, 0xffff00, v59
	v_and_b32_sdwa v60, v58, s2 dst_sel:DWORD dst_unused:UNUSED_PAD src0_sel:WORD_1 src1_sel:DWORD
	v_lshlrev_b32_e32 v56, 8, v58
	v_or_b32_e32 v58, v0, v59
	v_or_b32_e32 v57, v57, v60
	v_and_b32_e32 v59, 0xffffff00, v61
	v_lshlrev_b32_e32 v60, 16, v62
	v_and_b32_e32 v61, 0xffff0000, v62
	v_lshlrev_b32_e32 v62, 16, v63
	v_and_b32_e32 v63, 0xffff0000, v63
	v_mul_f32_e32 v0, v63, v63
	s_waitcnt vmcnt(7)
	v_lshrrev_b32_e32 v69, 8, v69
	v_pk_fma_f32 v[96:97], v[62:63], v[62:63], v[0:1] op_sel_hi:[1,1,0]
	s_waitcnt vmcnt(6)
	v_lshlrev_b32_e32 v0, 24, v75
	v_lshlrev_b32_e32 v67, 16, v74
	v_and_b32_e32 v69, 0xffff00, v69
	v_and_b32_sdwa v74, v68, s2 dst_sel:DWORD dst_unused:UNUSED_PAD src0_sel:WORD_1 src1_sel:DWORD
	v_lshlrev_b32_e32 v66, 8, v68
	v_or_b32_e32 v68, v0, v69
	v_or_b32_e32 v67, v67, v74
	v_and_b32_e32 v69, 0xffffff00, v75
	v_lshlrev_b32_e32 v75, 16, v73
	v_lshlrev_b32_e32 v74, 16, v72
	v_and_b32_e32 v73, 0xffff0000, v73
	v_and_b32_e32 v72, 0xffff0000, v72
	v_pk_mul_f32 v[76:77], v[72:73], v[72:73]
	s_waitcnt vmcnt(5)
	v_lshlrev_b32_e32 v92, 16, v78
	v_pk_fma_f32 v[100:101], v[74:75], v[74:75], v[76:77]
	v_lshl_add_u64 v[76:77], s[0:1], 0, v[44:45]
	v_lshl_add_u64 v[70:71], s[0:1], 0, v[46:47]
	v_and_b32_e32 v93, 0xffff0000, v78
	v_lshlrev_b32_e32 v94, 16, v79
	v_and_b32_e32 v95, 0xffff0000, v79
	v_mov_b32_e32 v104, v96
	v_pk_add_f32 v[100:101], v[100:101], v[100:101] op_sel:[0,1] op_sel_hi:[1,0]
	s_waitcnt vmcnt(4)
	v_lshrrev_b32_e32 v83, 8, v83
	v_lshlrev_b32_e32 v80, 8, v82
	s_waitcnt vmcnt(3)
	v_lshlrev_b32_e32 v0, 24, v85
	v_lshlrev_b32_e32 v81, 16, v84
	v_and_b32_e32 v83, 0xffff00, v83
	v_and_b32_sdwa v82, v82, s2 dst_sel:DWORD dst_unused:UNUSED_PAD src0_sel:WORD_1 src1_sel:DWORD
	v_or_b32_e32 v84, v0, v83
	v_or_b32_e32 v81, v81, v82
	s_waitcnt vmcnt(2)
	v_lshlrev_b32_e32 v91, 16, v86
	v_mov_b32_e32 v105, v91
	v_and_b32_e32 v85, 0xffffff00, v85
	s_waitcnt vmcnt(1)
	v_lshrrev_b32_e32 v83, 8, v167
	s_waitcnt vmcnt(0)
	v_lshlrev_b32_e32 v0, 24, v89
	v_and_b32_e32 v83, 0xffff00, v83
	v_lshlrev_b32_e32 v78, 8, v166
	v_lshlrev_b32_e32 v79, 16, v88
	v_and_b32_sdwa v88, v166, s2 dst_sel:DWORD dst_unused:UNUSED_PAD src0_sel:WORD_1 src1_sel:DWORD
	v_or_b32_e32 v82, v0, v83
	v_mul_f32_e32 v0, v61, v61
	v_pk_fma_f32 v[102:103], v[60:61], v[60:61], v[0:1] op_sel_hi:[1,1,0]
	v_and_b32_e32 v83, 0xffffff00, v89
	v_and_b32_e32 v89, 0xffff0000, v86
	v_mov_b32_e32 v90, v102
	v_or_b32_e32 v79, v79, v88
	v_mul_f32_e32 v88, v89, v89
	v_pk_add_f32 v[96:97], v[102:103], v[96:97]
	v_pk_mul_f32 v[102:103], v[90:91], v[104:105]
	v_mov_b32_e32 v101, v88
	v_mov_b32_e32 v97, v103
	v_mul_f32_e32 v0, v93, v93
	v_lshlrev_b32_e32 v86, 16, v87
	v_and_b32_e32 v87, 0xffff0000, v87
	v_pk_add_f32 v[96:97], v[96:97], v[100:101]
	v_pk_fma_f32 v[100:101], v[92:93], v[92:93], v[0:1] op_sel_hi:[1,1,0]
	v_mul_f32_e32 v0, v95, v95
	v_mul_f32_e32 v99, v86, v86
	v_mul_f32_e32 v106, v87, v87
	v_pk_fma_f32 v[102:103], v[94:95], v[94:95], v[0:1] op_sel_hi:[1,1,0]
	v_mov_b32_e32 v101, v99
	v_mov_b32_e32 v103, v106
	v_pk_add_f32 v[100:101], v[100:101], v[102:103]
	v_and_b32_e32 v0, 64, v230
	v_pk_add_f32 v[96:97], v[96:97], v[100:101]
	v_add_u32_e32 v100, 64, v0
	v_xor_b32_e32 v0, 1, v230
	v_cmp_lt_i32_e32 vcc, v0, v100
	v_add_f32_e32 v88, v96, v97
	s_mov_b32 s2, 0xf800000
	v_cndmask_b32_e32 v0, v230, v0, vcc
	v_lshlrev_b32_e32 v0, 2, v0
	s_nop 1
	v_add_f32_dpp v88, v88, v88 quad_perm:[1,0,3,2] row_mask:0xf bank_mask:0xf
	v_xor_b32_e32 v90, 2, v230
	v_cmp_lt_i32_e32 vcc, v90, v100
	s_nop 1
	v_cndmask_b32_e32 v90, v230, v90, vcc
	v_lshlrev_b32_e32 v90, 2, v90
	s_nop 1
	v_add_f32_dpp v88, v88, v88 quad_perm:[2,3,0,1] row_mask:0xf bank_mask:0xf
	v_xor_b32_e32 v96, 4, v230
	v_cmp_lt_i32_e32 vcc, v96, v100
	s_nop 1
	v_cndmask_b32_e32 v96, v230, v96, vcc
	v_lshlrev_b32_e32 v96, 2, v96
	s_nop 1
	v_add_f32_dpp v88, v88, v88 row_half_mirror row_mask:0xf bank_mask:0xf
	v_xor_b32_e32 v97, 8, v230
	v_cmp_lt_i32_e32 vcc, v97, v100
	s_nop 1
	v_cndmask_b32_e32 v97, v230, v97, vcc
	v_lshlrev_b32_e32 v97, 2, v97
	s_nop 1
	v_add_f32_dpp v88, v88, v88 row_mirror row_mask:0xf bank_mask:0xf
	v_xor_b32_e32 v99, 16, v230
	v_cmp_lt_i32_e32 vcc, v99, v100
	s_nop 1
	v_cndmask_b32_e32 v99, v230, v99, vcc
	v_lshlrev_b32_e32 v99, 2, v99
	ds_bpermute_b32 v101, v99, v88
	s_waitcnt lgkmcnt(0)
; __device__ __forceinline__ void ew_phase(const Frame& F, const bf16_t* f, const float* gpost, float alpha, const float* hin, float* hout, const float* gpre, bf16_t* xn, ...
;     ...
;         const float rstd = alpha / sqrtf(wave_sum(s) * (1.f / DM) + RMS_EPS);
;         float s2 = 0.f; f32x4* ho = (f32x4*)(hout + (size_t)m * DM) + F.lane;
; #pragma unroll
;         for (int j = 0; j < 4; ++j) { hv[j] = hv[j] + fv[j] * rstd * gp[j]; if (out24) store24(h24 + (size_t)m * (DM * 3), F.lane + 64 * j, hv[j]); else ho[64 * j] = hv[j]; s2 += (hv[j].x * hv[j].x + hv[j].y * hv[j].y) + (hv[j].z * hv[j].z + hv[j].w * hv[j].w); }
;         if (gpre) {
;             const float r2 = 1.0f / sqrtf(wave_sum(s2) * (1.f / DM) + RMS_EPS);
	v_add_f32_e32 v88, v88, v101
	v_xor_b32_e32 v101, 32, v230
	v_cmp_lt_i32_e32 vcc, v101, v100
	s_nop 1
	v_cndmask_b32_e32 v100, v230, v101, vcc
	v_lshlrev_b32_e32 v100, 2, v100
	ds_bpermute_b32 v101, v100, v88
	s_waitcnt lgkmcnt(0)
	v_add_f32_e32 v88, v88, v101
	v_fmamk_f32 v88, v88, 0x3a800000, v225
	v_cmp_gt_f32_e32 vcc, s2, v88
	v_mul_f32_e32 v101, 0x4f800000, v88
	s_nop 0
	v_cndmask_b32_e32 v88, v88, v101, vcc
	v_sqrt_f32_e32 v101, v88
	s_nop 0
	v_add_u32_e32 v102, -1, v101
	v_fma_f32 v103, -v102, v101, v88
	v_cmp_ge_f32_e64 s[0:1], 0, v103
	v_add_u32_e32 v103, 1, v101
	s_nop 0
	v_cndmask_b32_e64 v102, v101, v102, s[0:1]
	v_fma_f32 v101, -v103, v101, v88
	v_cmp_lt_f32_e64 s[0:1], 0, v101
	s_nop 1
	v_cndmask_b32_e64 v101, v102, v103, s[0:1]
	v_mul_f32_e32 v102, 0x37800000, v101
	v_cndmask_b32_e32 v101, v101, v102, vcc
	v_cmp_class_f32_e32 vcc, v88, v226
	s_nop 1
	v_cndmask_b32_e32 v88, v101, v88, vcc
	v_div_scale_f32 v101, s[0:1], v88, v88, 0.5
	v_rcp_f32_e32 v102, v101
	s_movk_i32 s0, 0x7f
	s_mov_b32 s1, 0x7060503
	v_fma_f32 v103, -v101, v102, 1.0
	v_fmac_f32_e32 v102, v103, v102
	v_div_scale_f32 v103, vcc, 0.5, v88, 0.5
	v_mul_f32_e32 v104, v103, v102
	v_fma_f32 v105, -v101, v104, v103
	v_fmac_f32_e32 v104, v105, v102
	v_fma_f32 v101, -v101, v104, v103
	v_div_fmas_f32 v101, v101, v102, v104
	v_div_fixup_f32 v102, v101, v88, 0.5
	v_pk_mul_f32 v[60:61], v[102:103], v[60:61] op_sel_hi:[0,1]
	v_pk_mul_f32 v[62:63], v[102:103], v[62:63] op_sel_hi:[0,1]
	v_pk_fma_f32 v[58:59], v[4:5], v[62:63], v[58:59]
	v_pk_fma_f32 v[56:57], v[2:3], v[60:61], v[56:57]
	v_bfe_u32 v63, v58, 8, 1
	v_bfe_u32 v61, v57, 8, 1
	v_bfe_u32 v60, v56, 8, 1
	v_add3_u32 v61, v57, v61, s0
	v_add3_u32 v63, v58, v63, s0
	v_bfe_u32 v101, v59, 8, 1
	v_add3_u32 v60, v56, v60, s0
	v_lshrrev_b32_e32 v62, 8, v61
	v_lshrrev_b32_e32 v88, 8, v63
	v_add3_u32 v101, v59, v101, s0
	v_alignbit_b32 v60, v62, v60, 8
	v_alignbit_b32 v61, v88, v61, 16
	v_perm_b32 v62, v101, v63, s1
	global_store_dwordx3 v[54:55], v[60:62], off nt
	v_pk_mul_f32 v[54:55], v[58:59], v[58:59]
	v_mov_b32_e32 v88, v91
	v_pk_mul_f32 v[60:61], v[56:57], v[56:57]
	s_nop 0
	v_pk_mov_b32 v[62:63], v[60:61], v[54:55] op_sel:[1,0]
	v_mov_b32_e32 v61, v55
	v_pk_add_f32 v[54:55], v[60:61], v[62:63]
	s_nop 0
	v_pk_add_f32 v[62:63], v[54:55], v[54:55] op_sel_hi:[0,1]
	v_mov_b32_e32 v54, v74
	v_mov_b32_e32 v55, v72
	v_mov_b32_e32 v72, v75
	v_pk_mul_f32 v[60:61], v[102:103], v[54:55] op_sel_hi:[0,1]
	v_pk_mul_f32 v[54:55], v[102:103], v[72:73] op_sel_hi:[0,1]
	v_pk_fma_f32 v[54:55], v[8:9], v[54:55], v[68:69]
	v_pk_fma_f32 v[60:61], v[6:7], v[60:61], v[66:67]
	v_bfe_u32 v68, v54, 8, 1
	v_bfe_u32 v66, v61, 8, 1
	v_bfe_u32 v62, v60, 8, 1
	v_add3_u32 v67, v61, v66, s0
	v_add3_u32 v68, v54, v68, s0
	v_bfe_u32 v72, v55, 8, 1
	v_add3_u32 v62, v60, v62, s0
	v_lshrrev_b32_e32 v66, 8, v67
	v_lshrrev_b32_e32 v69, 8, v68
	v_add3_u32 v72, v55, v72, s0
	v_alignbit_b32 v66, v66, v62, 8
	v_alignbit_b32 v67, v69, v67, 16
	v_perm_b32 v68, v72, v68, s1
	global_store_dwordx3 v[64:65], v[66:68], off nt
	v_pk_mul_f32 v[64:65], v[54:55], v[54:55]
	s_nop 0
	v_pk_mul_f32 v[66:67], v[60:61], v[60:61]
	s_nop 0
	v_pk_mov_b32 v[68:69], v[66:67], v[64:65] op_sel:[1,0]
	v_mov_b32_e32 v67, v65
	v_pk_add_f32 v[64:65], v[66:67], v[68:69]
	v_pk_mul_f32 v[66:67], v[102:103], v[92:93] op_sel_hi:[0,1]
	v_pk_add_f32 v[68:69], v[64:65], v[64:65] op_sel_hi:[0,1]
	v_pk_mul_f32 v[64:65], v[102:103], v[94:95] op_sel_hi:[0,1]
	v_pk_fma_f32 v[64:65], v[20:21], v[64:65], v[84:85]
	v_pk_fma_f32 v[72:73], v[18:19], v[66:67], v[80:81]
	v_bfe_u32 v68, v64, 8, 1
	v_bfe_u32 v66, v73, 8, 1
	v_bfe_u32 v62, v72, 8, 1
	v_add3_u32 v67, v73, v66, s0
	v_add3_u32 v68, v64, v68, s0
	v_bfe_u32 v75, v65, 8, 1
	v_add3_u32 v62, v72, v62, s0
	v_lshrrev_b32_e32 v66, 8, v67
	v_lshrrev_b32_e32 v74, 8, v68
	v_add3_u32 v75, v65, v75, s0
	v_alignbit_b32 v66, v66, v62, 8
	v_alignbit_b32 v67, v74, v67, 16
	v_perm_b32 v68, v75, v68, s1
	global_store_dwordx3 v[76:77], v[66:68], off nt
	v_pk_mul_f32 v[74:75], v[86:87], v[102:103] op_sel_hi:[1,0]
	v_mul_f32_e32 v62, v72, v72
	v_pk_mul_f32 v[66:67], v[88:89], v[102:103] op_sel_hi:[1,0]
	v_pk_fma_f32 v[74:75], v[24:25], v[74:75], v[82:83]
	v_pk_fma_f32 v[76:77], v[22:23], v[66:67], v[78:79]
	v_pk_fma_f32 v[80:81], v[72:73], v[72:73], v[62:63] op_sel_hi:[1,1,0]
	v_mul_f32_e32 v62, v64, v64
	v_bfe_u32 v66, v77, 8, 1
	v_bfe_u32 v68, v74, 8, 1
	v_pk_fma_f32 v[84:85], v[64:65], v[64:65], v[62:63] op_sel_hi:[1,1,0]
	v_bfe_u32 v62, v76, 8, 1
	v_add3_u32 v67, v77, v66, s0
	v_add3_u32 v68, v74, v68, s0
	v_bfe_u32 v79, v75, 8, 1
	v_add3_u32 v62, v76, v62, s0
	v_lshrrev_b32_e32 v66, 8, v67
	v_lshrrev_b32_e32 v78, 8, v68
	v_add3_u32 v79, v75, v79, s0
	v_alignbit_b32 v66, v66, v62, 8
	v_alignbit_b32 v67, v78, v67, 16
	v_perm_b32 v68, v79, v68, s1
	global_store_dwordx3 v[70:71], v[66:68], off nt
	v_mul_f32_e32 v80, v76, v76
	v_mul_f32_e32 v84, v77, v77
	v_mul_f32_e32 v62, v75, v75
	v_mul_f32_e32 v68, v74, v74
	v_pk_add_f32 v[66:67], v[80:81], v[84:85]
	v_pk_add_f32 v[62:63], v[62:63], v[68:69]
	v_lshl_add_u64 v[78:79], v[36:37], 0, s[12:13]
	v_pk_add_f32 v[62:63], v[66:67], v[62:63]
	s_nop 0
	v_add_f32_e32 v62, v62, v63
	s_nop 1
	v_add_f32_dpp v62, v62, v62 quad_perm:[1,0,3,2] row_mask:0xf bank_mask:0xf
	s_nop 1
	v_add_f32_dpp v62, v62, v62 quad_perm:[2,3,0,1] row_mask:0xf bank_mask:0xf
	s_nop 1
	v_add_f32_dpp v62, v62, v62 row_half_mirror row_mask:0xf bank_mask:0xf
	s_nop 1
	v_add_f32_dpp v62, v62, v62 row_mirror row_mask:0xf bank_mask:0xf
	ds_bpermute_b32 v63, v99, v62
	s_waitcnt lgkmcnt(0)
	v_add_f32_e32 v62, v62, v63
	ds_bpermute_b32 v63, v100, v62
	s_waitcnt lgkmcnt(0)
; #define LAS __attribute__((address_space(3)))
; __device__ __forceinline__ unsigned cvt_pk_bf16(float lo, float hi) { f32x2 v = {lo, hi}; bf16x2_t b = __builtin_convertvector(v, bf16x2_t); return __builtin_bit_cast(unsigned, b); }
; __device__ __forceinline__ void ew_phase(const Frame& F, const bf16_t* f, const float* gpost, float alpha, const float* hin, float* hout, const float* gpre, bf16_t* xn, ...
;     ...
;             const float r2 = 1.0f / sqrtf(wave_sum(s2) * (1.f / DM) + RMS_EPS);
;             u32x2* o8 = (u32x2*)(xn + (size_t)m * DM) + F.lane;
; #pragma unroll
;             for (int j = 0; j < 4; ++j) { hv[j] = hv[j] * r2 * gq[j]; u32x2 w; w.x = cvt_pk_bf16(hv[j].x, hv[j].y); w.y = cvt_pk_bf16(hv[j].z, hv[j].w); o8[64 * j] = w; }
;             if (win_l) {
;                 float a8[8];
; #pragma unroll
;                 for (int k = 0; k < 8; ++k) a8[k] = 0.f;
; #pragma unroll
;                 for (int k = 0; k < 8; ++k)
; #pragma unroll
;                     for (int j = 0; j < 4; ++j) { const f32x4 w4 = *(const LAS f32x4*)(WF + k * DM + 256 * j + 4 * F.lane);
;                         a8[k] += (hv[j].x * w4.x + hv[j].y * w4.y) + (hv[j].z * w4.z + hv[j].w * w4.w); }
	v_add_f32_e32 v62, v62, v63
	v_fmamk_f32 v62, v62, 0x3a800000, v225
	v_cmp_gt_f32_e32 vcc, s2, v62
	v_mul_f32_e32 v63, 0x4f800000, v62
	s_nop 0
	v_cndmask_b32_e32 v62, v62, v63, vcc
	v_sqrt_f32_e32 v63, v62
	s_nop 0
	v_add_u32_e32 v66, -1, v63
	v_fma_f32 v67, -v66, v63, v62
	v_cmp_ge_f32_e64 s[0:1], 0, v67
	v_add_u32_e32 v67, 1, v63
	s_nop 0
	v_cndmask_b32_e64 v66, v63, v66, s[0:1]
	v_fma_f32 v63, -v67, v63, v62
	v_cmp_lt_f32_e64 s[0:1], 0, v63
	s_nop 1
	v_cndmask_b32_e64 v63, v66, v67, s[0:1]
	v_mul_f32_e32 v66, 0x37800000, v63
	v_cndmask_b32_e32 v63, v63, v66, vcc
	v_cmp_class_f32_e32 vcc, v62, v226
	s_nop 1
	v_cndmask_b32_e32 v62, v63, v62, vcc
	v_div_scale_f32 v63, s[0:1], v62, v62, 1.0
	v_rcp_f32_e32 v66, v63
	s_nop 0
	v_fma_f32 v67, -v63, v66, 1.0
	v_fmac_f32_e32 v66, v67, v66
	v_div_scale_f32 v67, vcc, 1.0, v62, 1.0
	v_mul_f32_e32 v68, v67, v66
	v_fma_f32 v69, -v63, v68, v67
	v_fmac_f32_e32 v68, v69, v66
	v_fma_f32 v63, -v63, v68, v67
	v_div_fmas_f32 v63, v63, v66, v68
	v_div_fixup_f32 v70, v63, v62, 1.0
	v_pk_mul_f32 v[56:57], v[56:57], v[70:71] op_sel_hi:[1,0]
	v_pk_mul_f32 v[58:59], v[58:59], v[70:71] op_sel_hi:[1,0]
	v_pk_mul_f32 v[68:69], v[10:11], v[56:57]
	v_pk_mul_f32 v[66:67], v[12:13], v[58:59]
	v_cvt_pk_bf16_f32 v56, v68, v69
	v_cvt_pk_bf16_f32 v57, v66, v67
	global_store_dwordx2 v[78:79], v[56:57], off nt
	v_pk_mul_f32 v[56:57], v[60:61], v[70:71] op_sel_hi:[1,0]
	v_pk_mul_f32 v[54:55], v[54:55], v[70:71] op_sel_hi:[1,0]
	v_pk_mul_f32 v[62:63], v[14:15], v[56:57]
	v_pk_mul_f32 v[58:59], v[16:17], v[54:55]
	v_cvt_pk_bf16_f32 v54, v62, v63
	v_cvt_pk_bf16_f32 v55, v58, v59
	global_store_dwordx2 v[78:79], v[54:55], off offset:512 nt
	v_pk_mul_f32 v[54:55], v[72:73], v[70:71] op_sel_hi:[1,0]
	v_pk_mul_f32 v[56:57], v[64:65], v[70:71] op_sel_hi:[1,0]
	v_pk_mul_f32 v[64:65], v[26:27], v[54:55]
	v_pk_mul_f32 v[60:61], v[28:29], v[56:57]
	v_cvt_pk_bf16_f32 v54, v64, v65
	v_cvt_pk_bf16_f32 v55, v60, v61
	global_store_dwordx2 v[78:79], v[54:55], off offset:1024 nt
	v_pk_mul_f32 v[56:57], v[76:77], v[70:71] op_sel_hi:[1,0]
	v_pk_mul_f32 v[54:55], v[74:75], v[70:71] op_sel_hi:[1,0]
	v_pk_mul_f32 v[56:57], v[30:31], v[56:57]
	v_pk_mul_f32 v[54:55], v[32:33], v[54:55]
	v_cvt_pk_bf16_f32 v70, v56, v57
	v_cvt_pk_bf16_f32 v71, v54, v55
	global_store_dwordx2 v[78:79], v[70:71], off offset:1536 nt
	v_add_u32_e32 v70, 0, v43
	v_add_u32_e32 v70, 0x18000, v70
	ds_read_b128 v[72:75], v70
	s_waitcnt lgkmcnt(0)
	v_mul_f32_e32 v71, v73, v69
	v_fmac_f32_e32 v71, v72, v68
	v_mul_f32_e32 v72, v75, v67
	v_fmac_f32_e32 v72, v74, v66
	v_add_f32_e32 v71, v71, v72
	ds_read_b128 v[72:75], v70 offset:1024
	v_add_f32_e32 v71, 0, v71
	s_waitcnt lgkmcnt(0)
	v_mul_f32_e32 v73, v73, v63
	v_fmac_f32_e32 v73, v72, v62
	v_mul_f32_e32 v72, v75, v59
	v_fmac_f32_e32 v72, v74, v58
	v_add_f32_e32 v72, v73, v72
	v_add_f32_e32 v71, v72, v71
	ds_read_b128 v[72:75], v70 offset:2048
	s_waitcnt lgkmcnt(0)
	v_mul_f32_e32 v73, v73, v65
	v_fmac_f32_e32 v73, v72, v64
	v_mul_f32_e32 v72, v75, v61
	v_fmac_f32_e32 v72, v74, v60
	v_add_f32_e32 v72, v73, v72
	v_add_f32_e32 v71, v72, v71
	ds_read_b128 v[72:75], v70 offset:3072
	s_waitcnt lgkmcnt(0)
	v_mul_f32_e32 v73, v73, v57
	v_fmac_f32_e32 v73, v72, v56
	v_mul_f32_e32 v72, v75, v55
	v_fmac_f32_e32 v72, v74, v54
	v_add_f32_e32 v72, v73, v72
	v_add_f32_e32 v71, v72, v71
	ds_read_b128 v[72:75], v70 offset:4096
	s_waitcnt lgkmcnt(0)
	v_mul_f32_e32 v73, v73, v69
	v_fmac_f32_e32 v73, v72, v68
	v_mul_f32_e32 v72, v75, v67
	v_fmac_f32_e32 v72, v74, v66
	v_add_f32_e32 v72, v73, v72
	v_add_f32_e32 v76, 0, v72
	ds_read_b128 v[72:75], v70 offset:5120
	s_waitcnt lgkmcnt(0)
	v_mul_f32_e32 v73, v73, v63
	v_fmac_f32_e32 v73, v72, v62
	v_mul_f32_e32 v72, v75, v59
	v_fmac_f32_e32 v72, v74, v58
	v_add_f32_e32 v72, v73, v72
	v_add_f32_e32 v76, v72, v76
	ds_read_b128 v[72:75], v70 offset:6144
	s_waitcnt lgkmcnt(0)
	v_mul_f32_e32 v73, v73, v65
	v_fmac_f32_e32 v73, v72, v64
	v_mul_f32_e32 v72, v75, v61
	v_fmac_f32_e32 v72, v74, v60
	v_add_f32_e32 v72, v73, v72
	v_add_f32_e32 v76, v72, v76
	ds_read_b128 v[72:75], v70 offset:7168
	s_waitcnt lgkmcnt(0)
	v_mul_f32_e32 v73, v73, v57
	v_fmac_f32_e32 v73, v72, v56
	v_mul_f32_e32 v72, v75, v55
	v_fmac_f32_e32 v72, v74, v54
	v_add_f32_e32 v72, v73, v72
	v_add_f32_e32 v72, v72, v76
	ds_read_b128 v[74:77], v70 offset:8192
	s_waitcnt lgkmcnt(0)
	v_mul_f32_e32 v73, v75, v69
	v_fmac_f32_e32 v73, v74, v68
	v_mul_f32_e32 v74, v77, v67
	v_fmac_f32_e32 v74, v76, v66
	v_add_f32_e32 v73, v73, v74
	ds_read_b128 v[74:77], v70 offset:9216
	v_add_f32_e32 v73, 0, v73
	s_waitcnt lgkmcnt(0)
	v_mul_f32_e32 v75, v63, v75
	v_fmac_f32_e32 v75, v62, v74
	v_mul_f32_e32 v74, v59, v77
	v_fmac_f32_e32 v74, v58, v76
	v_add_f32_e32 v74, v75, v74
	v_add_f32_e32 v73, v74, v73
	ds_read_b128 v[74:77], v70 offset:10240
	s_waitcnt lgkmcnt(0)
	v_mul_f32_e32 v75, v65, v75
	v_fmac_f32_e32 v75, v64, v74
	v_mul_f32_e32 v74, v61, v77
	v_fmac_f32_e32 v74, v60, v76
	v_add_f32_e32 v74, v75, v74
	v_add_f32_e32 v73, v74, v73
	ds_read_b128 v[74:77], v70 offset:11264
	s_waitcnt lgkmcnt(0)
	v_mul_f32_e32 v75, v57, v75
	v_fmac_f32_e32 v75, v56, v74
	v_mul_f32_e32 v74, v55, v77
	v_fmac_f32_e32 v74, v54, v76
	v_add_f32_e32 v74, v75, v74
	v_add_f32_e32 v73, v74, v73
	ds_read_b128 v[74:77], v70 offset:12288
	s_waitcnt lgkmcnt(0)
	v_mul_f32_e32 v75, v69, v75
	v_fmac_f32_e32 v75, v68, v74
	v_mul_f32_e32 v74, v67, v77
	v_fmac_f32_e32 v74, v66, v76
	v_add_f32_e32 v74, v75, v74
	v_add_f32_e32 v78, 0, v74
	ds_read_b128 v[74:77], v70 offset:13312
	s_waitcnt lgkmcnt(0)
; #define LAS __attribute__((address_space(3)))
; __device__ __forceinline__ void ew_phase(const Frame& F, const bf16_t* f, const float* gpost, float alpha, const float* hin, float* hout, const float* gpre, bf16_t* xn, ...
;     ...
;                     for (int j = 0; j < 4; ++j) { const f32x4 w4 = *(const LAS f32x4*)(WF + k * DM + 256 * j + 4 * F.lane);
;                         a8[k] += (hv[j].x * w4.x + hv[j].y * w4.y) + (hv[j].z * w4.z + hv[j].w * w4.w); }
;                 const bool b5 = (F.lane & 32) != 0, b4 = (F.lane & 16) != 0, b3 = (F.lane & 8) != 0;
;                 float r4[4], r2v[2], r1;
; #pragma unroll
;                 for (int k = 0; k < 4; ++k) { const float keep = b5 ? a8[k + 4] : a8[k], give = b5 ? a8[k] : a8[k + 4]; r4[k] = keep + __shfl_xor(give, 32); }
; #pragma unroll
;                 for (int k = 0; k < 2; ++k) { const float keep = b4 ? r4[k + 2] : r4[k], give = b4 ? r4[k] : r4[k + 2]; r2v[k] = keep + __shfl_xor(give, 16); }
;                 { const float keep = b3 ? r2v[1] : r2v[0], give = b3 ? r2v[0] : r2v[1]; r1 = keep + __shfl_xor(give, 8); }
;                 r1 += __shfl_xor(r1, 4); r1 += __shfl_xor(r1, 2); r1 += __shfl_xor(r1, 1);
;                 if ((F.lane & 7) == 0) { const int k = (b5 ? 4 : 0) + (b4 ? 2 : 0) + (b3 ? 1 : 0); const float x = r1 + bfl[k];
	v_mul_f32_e32 v75, v63, v75
	v_fmac_f32_e32 v75, v62, v74
	v_mul_f32_e32 v74, v59, v77
	v_fmac_f32_e32 v74, v58, v76
	v_add_f32_e32 v74, v75, v74
	v_add_f32_e32 v78, v78, v74
	ds_read_b128 v[74:77], v70 offset:14336
	s_waitcnt lgkmcnt(0)
	v_mul_f32_e32 v75, v65, v75
	v_fmac_f32_e32 v75, v64, v74
	v_mul_f32_e32 v74, v61, v77
	v_fmac_f32_e32 v74, v60, v76
	v_add_f32_e32 v74, v75, v74
	v_add_f32_e32 v78, v78, v74
	ds_read_b128 v[74:77], v70 offset:15360
	s_waitcnt lgkmcnt(0)
	v_mul_f32_e32 v75, v57, v75
	v_fmac_f32_e32 v75, v56, v74
	v_mul_f32_e32 v74, v55, v77
	v_fmac_f32_e32 v74, v54, v76
	v_add_f32_e32 v74, v75, v74
	v_add_f32_e32 v74, v78, v74
	ds_read_b128 v[76:79], v70 offset:16384
	s_waitcnt lgkmcnt(0)
	v_mul_f32_e32 v75, v69, v77
	v_fmac_f32_e32 v75, v68, v76
	v_mul_f32_e32 v76, v67, v79
	v_fmac_f32_e32 v76, v66, v78
	v_add_f32_e32 v75, v75, v76
	ds_read_b128 v[76:79], v70 offset:17408
	v_add_f32_e32 v75, 0, v75
	s_waitcnt lgkmcnt(0)
	v_mul_f32_e32 v77, v63, v77
	v_fmac_f32_e32 v77, v62, v76
	v_mul_f32_e32 v76, v59, v79
	v_fmac_f32_e32 v76, v58, v78
	v_add_f32_e32 v76, v77, v76
	v_add_f32_e32 v75, v75, v76
	ds_read_b128 v[76:79], v70 offset:18432
	s_waitcnt lgkmcnt(0)
	v_mul_f32_e32 v77, v65, v77
	v_fmac_f32_e32 v77, v64, v76
	v_mul_f32_e32 v76, v61, v79
	v_fmac_f32_e32 v76, v60, v78
	v_add_f32_e32 v76, v77, v76
	v_add_f32_e32 v75, v75, v76
	ds_read_b128 v[76:79], v70 offset:19456
	s_waitcnt lgkmcnt(0)
	v_mul_f32_e32 v77, v57, v77
	v_fmac_f32_e32 v77, v56, v76
	v_mul_f32_e32 v76, v55, v79
	v_fmac_f32_e32 v76, v54, v78
	v_add_f32_e32 v76, v77, v76
	v_add_f32_e32 v75, v75, v76
	ds_read_b128 v[76:79], v70 offset:20480
	s_waitcnt lgkmcnt(0)
	v_mul_f32_e32 v77, v69, v77
	v_fmac_f32_e32 v77, v68, v76
	v_mul_f32_e32 v76, v67, v79
	v_fmac_f32_e32 v76, v66, v78
	v_add_f32_e32 v76, v77, v76
	v_add_f32_e32 v80, 0, v76
	ds_read_b128 v[76:79], v70 offset:21504
	s_waitcnt lgkmcnt(0)
	v_mul_f32_e32 v77, v63, v77
	v_fmac_f32_e32 v77, v62, v76
	v_mul_f32_e32 v76, v59, v79
	v_fmac_f32_e32 v76, v58, v78
	v_add_f32_e32 v76, v77, v76
	v_add_f32_e32 v80, v80, v76
	ds_read_b128 v[76:79], v70 offset:22528
	s_waitcnt lgkmcnt(0)
	v_mul_f32_e32 v77, v65, v77
	v_fmac_f32_e32 v77, v64, v76
	v_mul_f32_e32 v76, v61, v79
	v_fmac_f32_e32 v76, v60, v78
	v_add_f32_e32 v76, v77, v76
	v_add_f32_e32 v80, v80, v76
	ds_read_b128 v[76:79], v70 offset:23552
	s_waitcnt lgkmcnt(0)
	v_mul_f32_e32 v77, v57, v77
	v_fmac_f32_e32 v77, v56, v76
	v_mul_f32_e32 v76, v55, v79
	v_fmac_f32_e32 v76, v54, v78
	v_add_f32_e32 v76, v77, v76
	v_add_f32_e32 v80, v80, v76
	ds_read_b128 v[76:79], v70 offset:24576
	s_waitcnt lgkmcnt(0)
	v_mul_f32_e32 v77, v69, v77
	v_fmac_f32_e32 v77, v68, v76
	v_mul_f32_e32 v76, v67, v79
	v_fmac_f32_e32 v76, v66, v78
	v_add_f32_e32 v76, v77, v76
	v_add_f32_e32 v81, 0, v76
	ds_read_b128 v[76:79], v70 offset:25600
	s_waitcnt lgkmcnt(0)
	v_mul_f32_e32 v77, v63, v77
	v_fmac_f32_e32 v77, v62, v76
	v_mul_f32_e32 v76, v59, v79
	v_fmac_f32_e32 v76, v58, v78
	v_add_f32_e32 v76, v77, v76
	v_add_f32_e32 v81, v81, v76
	ds_read_b128 v[76:79], v70 offset:26624
	s_waitcnt lgkmcnt(0)
	v_mul_f32_e32 v77, v65, v77
	v_fmac_f32_e32 v77, v64, v76
	v_mul_f32_e32 v76, v61, v79
	v_fmac_f32_e32 v76, v60, v78
	v_add_f32_e32 v76, v77, v76
	v_add_f32_e32 v81, v81, v76
	ds_read_b128 v[76:79], v70 offset:27648
	s_waitcnt lgkmcnt(0)
	v_mul_f32_e32 v77, v57, v77
	v_fmac_f32_e32 v77, v56, v76
	v_mul_f32_e32 v76, v55, v79
	v_fmac_f32_e32 v76, v54, v78
	v_add_f32_e32 v76, v77, v76
	v_add_f32_e32 v81, v81, v76
	ds_read_b128 v[76:79], v70 offset:28672
	s_waitcnt lgkmcnt(0)
	v_mul_f32_e32 v69, v69, v77
	v_mul_f32_e32 v67, v67, v79
	v_fmac_f32_e32 v69, v68, v76
	v_fmac_f32_e32 v67, v66, v78
	v_add_f32_e32 v66, v69, v67
	v_add_f32_e32 v76, 0, v66
	ds_read_b128 v[66:69], v70 offset:29696
	s_waitcnt lgkmcnt(0)
	v_mul_f32_e32 v63, v63, v67
	v_mul_f32_e32 v59, v59, v69
	v_fmac_f32_e32 v63, v62, v66
	v_fmac_f32_e32 v59, v58, v68
	ds_read_b128 v[66:69], v70 offset:30720
	v_add_f32_e32 v58, v63, v59
	v_add_f32_e32 v58, v76, v58
	s_waitcnt lgkmcnt(0)
	v_mul_f32_e32 v59, v65, v67
	v_mul_f32_e32 v61, v61, v69
	v_fmac_f32_e32 v59, v64, v66
	v_fmac_f32_e32 v61, v60, v68
	v_add_f32_e32 v59, v59, v61
	v_add_f32_e32 v62, v58, v59
	ds_read_b128 v[58:61], v70 offset:31744
	s_waitcnt lgkmcnt(0)
	v_mul_f32_e32 v57, v57, v59
	v_mul_f32_e32 v55, v55, v61
	v_fmac_f32_e32 v57, v56, v58
	v_fmac_f32_e32 v55, v54, v60
	v_cndmask_b32_e64 v56, v71, v75, s[36:37]
	v_add_f32_e32 v54, v57, v55
	ds_bpermute_b32 v56, v100, v56
	v_cndmask_b32_e64 v57, v72, v80, s[36:37]
	ds_bpermute_b32 v57, v100, v57
	v_cndmask_b32_e64 v58, v73, v81, s[36:37]
	ds_bpermute_b32 v58, v100, v58
	v_cndmask_b32_e64 v55, v75, v71, s[36:37]
	s_waitcnt lgkmcnt(2)
	v_add_f32_e32 v55, v55, v56
	v_cndmask_b32_e64 v56, v80, v72, s[36:37]
	v_add_f32_e32 v54, v62, v54
	s_waitcnt lgkmcnt(1)
	v_add_f32_e32 v56, v56, v57
	v_cndmask_b32_e64 v57, v81, v73, s[36:37]
	s_waitcnt lgkmcnt(0)
	v_add_f32_e32 v57, v57, v58
	v_cndmask_b32_e64 v58, v54, v74, s[36:37]
	v_cndmask_b32_e64 v54, v74, v54, s[36:37]
	ds_bpermute_b32 v54, v100, v54
	s_waitcnt lgkmcnt(0)
	v_add_f32_e32 v54, v58, v54
	v_cndmask_b32_e64 v58, v57, v55, s[38:39]
	v_cndmask_b32_e64 v55, v55, v57, s[38:39]
	v_cndmask_b32_e64 v57, v54, v56, s[38:39]
	v_cndmask_b32_e64 v54, v56, v54, s[38:39]
	ds_bpermute_b32 v55, v99, v55
	ds_bpermute_b32 v54, v99, v54
	s_waitcnt lgkmcnt(1)
	v_add_f32_e32 v55, v58, v55
	s_waitcnt lgkmcnt(0)
	v_add_f32_e32 v54, v57, v54
	v_cndmask_b32_e64 v56, v54, v55, s[40:41]
	v_cndmask_b32_e64 v54, v55, v54, s[40:41]
	ds_bpermute_b32 v54, v97, v54
	s_waitcnt lgkmcnt(0)
	v_add_f32_e32 v54, v56, v54
	ds_bpermute_b32 v55, v96, v54
	s_waitcnt lgkmcnt(0)
	v_add_f32_e32 v54, v54, v55
	ds_bpermute_b32 v55, v90, v54
	s_waitcnt lgkmcnt(0)
	v_add_f32_e32 v54, v54, v55
	ds_bpermute_b32 v0, v0, v54
	s_and_saveexec_b64 s[0:1], s[42:43]
	s_cbranch_execz .LBB0_207
; __device__ __forceinline__ void ew_phase(const Frame& F, const bf16_t* f, const float* gpost, float alpha, const float* hin, float* hout, const float* gpre, bf16_t* xn, ...
;     ...
;                 if ((F.lane & 7) == 0) { const int k = (b5 ? 4 : 0) + (b4 ? 2 : 0) + (b3 ? 1 : 0); const float x = r1 + bfl[k];
;                     const float ls = fminf(x, 0.f) - log1pf(expf(-fabsf(x))); logf[(size_t)k * T + m] = ls * LOG2E; logf[(size_t)T * 8 + (size_t)k * T + m] = 0.f; }
	global_load_dword v55, v[48:49], off
	s_waitcnt lgkmcnt(0)
	v_add_f32_e32 v0, v54, v0
	s_lshl_b64 s[2:3], s[10:11], 2
	s_waitcnt vmcnt(0)
	v_add_f32_e32 v0, v0, v55
	v_mul_f32_e64 v54, |v0|, s27
	v_fma_f32 v55, |v0|, s27, -v54
	v_rndne_f32_e32 v56, v54
	v_fma_f32 v55, |v0|, s35, v55
	v_sub_f32_e32 v54, v54, v56
	v_add_f32_e32 v54, v54, v55
	v_cvt_i32_f32_e32 v58, v56
	v_exp_f32_e32 v59, v54
	v_lshl_add_u64 v[54:55], v[50:51], 0, s[2:3]
	v_lshl_add_u64 v[56:57], v[52:53], 0, s[2:3]
	s_mov_b32 s2, 0x42ce8ed0
	v_ldexp_f32 v58, v59, v58
	v_cmp_ngt_f32_e64 vcc, |v0|, s2
	s_mov_b32 s2, 0xc2b17218
	v_min_f32_e32 v60, 0, v0
	v_cndmask_b32_e32 v58, 0, v58, vcc
	v_cmp_nlt_f32_e64 vcc, |v0|, s2
	s_mov_b32 s2, 0x3f2aaaab
	s_nop 0
	v_cndmask_b32_e32 v0, v107, v58, vcc
	v_add_f32_e32 v61, 1.0, v0
	v_add_f32_e32 v62, -1.0, v61
	v_frexp_mant_f32_e32 v63, v61
	v_cvt_f64_f32_e32 v[58:59], v61
	v_sub_f32_e32 v64, v62, v61
	v_frexp_exp_i32_f64_e32 v58, v[58:59]
	v_cmp_gt_f32_e32 vcc, s2, v63
	v_sub_f32_e32 v62, v0, v62
	v_add_f32_e32 v59, 1.0, v64
	v_subbrev_co_u32_e32 v58, vcc, 0, v58, vcc
	v_add_f32_e32 v59, v62, v59
	v_sub_u32_e32 v62, 0, v58
	v_cvt_f32_i32_e32 v58, v58
	v_ldexp_f32 v61, v61, v62
	v_ldexp_f32 v59, v59, v62
	v_add_f32_e32 v62, -1.0, v61
	v_add_f32_e32 v63, 1.0, v61
	v_add_f32_e32 v64, 1.0, v62
	v_add_f32_e32 v65, -1.0, v63
	v_sub_f32_e32 v64, v61, v64
	v_sub_f32_e32 v61, v61, v65
	v_mul_f32_e32 v65, 0x3f317218, v58
	v_add_f32_e32 v64, v59, v64
	v_add_f32_e32 v59, v59, v61
	s_mov_b32 s2, 0x3f317218
	v_fma_f32 v61, v58, s2, -v65
	v_add_f32_e32 v66, v62, v64
	v_add_f32_e32 v67, v63, v59
	v_fmac_f32_e32 v61, 0xb102e308, v58
	v_sub_f32_e32 v58, v62, v66
	v_sub_f32_e32 v62, v63, v67
	v_rcp_f32_e32 v63, v67
	v_add_f32_e32 v68, v65, v61
	v_add_f32_e32 v59, v59, v62
	v_sub_f32_e32 v62, v68, v65
	v_sub_f32_e32 v61, v61, v62
	v_mul_f32_e32 v62, v66, v63
	v_add_f32_e32 v58, v64, v58
	v_mul_f32_e32 v64, v67, v62
	v_fma_f32 v65, v62, v67, -v64
	v_fmac_f32_e32 v65, v62, v59
	v_add_f32_e32 v69, v64, v65
	v_sub_f32_e32 v70, v66, v69
	v_sub_f32_e32 v64, v69, v64
	v_sub_f32_e32 v66, v66, v70
	v_sub_f32_e32 v64, v64, v65
	v_sub_f32_e32 v65, v66, v69
	v_add_f32_e32 v58, v58, v65
	v_add_f32_e32 v58, v64, v58
	v_add_f32_e32 v64, v70, v58
	v_mul_f32_e32 v65, v63, v64
	v_sub_f32_e32 v66, v70, v64
	v_mul_f32_e32 v69, v67, v65
	v_add_f32_e32 v58, v58, v66
	v_add_f32_e32 v66, v62, v65
	v_fma_f32 v67, v65, v67, -v69
	v_sub_f32_e32 v62, v66, v62
	v_fmac_f32_e32 v67, v65, v59
	v_sub_f32_e32 v59, v65, v62
	v_add_f32_e32 v62, v69, v67
	v_sub_f32_e32 v65, v62, v69
	v_sub_f32_e32 v69, v64, v62
	v_sub_f32_e32 v64, v64, v69
	v_sub_f32_e32 v62, v64, v62
	v_sub_f32_e32 v65, v65, v67
	v_add_f32_e32 v58, v58, v62
	v_add_f32_e32 v58, v65, v58
	v_add_f32_e32 v58, v69, v58
	v_mul_f32_e32 v58, v63, v58
	v_add_f32_e32 v58, v59, v58
	v_add_f32_e32 v59, v66, v58
	v_mul_f32_e32 v62, v59, v59
	v_fmamk_f32 v65, v62, 0x3e9b6dac, v235
	v_sub_f32_e32 v63, v59, v66
	v_ldexp_f32 v64, v59, 1
	v_mul_f32_e32 v59, v59, v62
	v_fmaak_f32 v62, v62, v65, 0x3f2aaada
	v_mul_f32_e32 v59, v59, v62
	v_add_f32_e32 v62, v64, v59
	v_sub_f32_e32 v58, v58, v63
	v_sub_f32_e32 v63, v62, v64
	v_ldexp_f32 v58, v58, 1
	v_sub_f32_e32 v59, v59, v63
	v_add_f32_e32 v58, v58, v59
	v_add_f32_e32 v59, v62, v58
	v_sub_f32_e32 v62, v59, v62
	v_add_f32_e32 v63, v68, v59
	v_sub_f32_e32 v58, v58, v62
	v_sub_f32_e32 v62, v63, v68
	v_sub_f32_e32 v64, v63, v62
	v_sub_f32_e32 v59, v59, v62
	v_add_f32_e32 v62, v61, v58
	v_sub_f32_e32 v64, v68, v64
	v_sub_f32_e32 v65, v62, v61
	v_add_f32_e32 v59, v59, v64
	v_sub_f32_e32 v64, v62, v65
	v_sub_f32_e32 v58, v58, v65
	v_sub_f32_e32 v61, v61, v64
	v_add_f32_e32 v59, v62, v59
	v_add_f32_e32 v58, v58, v61
	v_add_f32_e32 v61, v63, v59
	v_sub_f32_e32 v62, v61, v63
	v_sub_f32_e32 v59, v59, v62
	v_add_f32_e32 v58, v58, v59
	s_mov_b32 s2, 0x7f800000
	v_add_f32_e32 v58, v61, v58
	v_cmp_neq_f32_e32 vcc, s2, v0
	s_mov_b32 s2, 0x33800000
	s_nop 0
	v_cndmask_b32_e32 v58, v107, v58, vcc
	v_cmp_lt_f32_e64 vcc, |v0|, s2
	s_nop 1
	v_cndmask_b32_e32 v0, v58, v0, vcc
	v_sub_f32_e32 v0, v60, v0
	v_mul_f32_e32 v0, 0x3fb8aa3b, v0
	global_store_dword v[54:55], v0, off
	global_store_dword v[56:57], v1, off
	s_branch .LBB0_207

; __device__ __forceinline__ float bf_lo(unsigned w) { return __uint_as_float(w << 16); }
; __device__ __forceinline__ float bf_hi(unsigned w) { return __uint_as_float(w & 0xffff0000u); }
; __device__ __forceinline__ void ew_phase(const Frame& F, const bf16_t* f, const float* gpost, float alpha, const float* hin, float* hout, const float* gpre, bf16_t* xn, ...
;     ...
;         const int m = prow0 >= 0 ? prow0 + F.wave * 8 + it_ : F.gw + it_ * F.NGW; if (m >= T) break;
;         const u32x2* fr = (const u32x2*)(f + (size_t)m * DM) + F.lane; const f32x4* hr = (const f32x4*)(hin + (size_t)m * DM) + F.lane;
;         f32x4 fv[4], hv[4]; float s = 0.f;
; #pragma unroll
;         for (int j = 0; j < 4; ++j) { const u32x2 w = fr[64 * j]; hv[j] = in24 ? load24(h24 + (size_t)m * (DM * 3), F.lane + 64 * j) : hr[64 * j]; fv[j] = (f32x4){bf_lo(w.x), bf_hi(w.x), bf_lo(w.y), bf_hi(w.y)};
;             s += (fv[j].x * fv[j].x + fv[j].y * fv[j].y) + (fv[j].z * fv[j].z + fv[j].w * fv[j].w); }
;         const float rstd = alpha / sqrtf(wave_sum(s) * (1.f / DM) + RMS_EPS);
.LBB0_812:
	v_readlane_b32 s0, v252, 11
	s_add_i32 s8, s2, s3
	v_readlane_b32 s1, v252, 12
	s_and_b64 s[0:1], s[0:1], exec
	s_cselect_b32 s8, s8, s12
	s_cmpk_gt_i32 s8, 0x3fff
	s_mov_b64 s[0:1], -1
	s_cbranch_scc1 .LBB0_811
	s_ashr_i32 s9, s8, 31
	s_lshl_b64 s[0:1], s[8:9], 11
	v_lshl_add_u64 v[78:79], v[36:37], 0, s[0:1]
	s_mul_i32 s0, s8, 0xc00
	s_mul_hi_i32 s1, s8, 0xc00
	s_add_u32 s0, s25, s0
	s_addc_u32 s1, s27, s1
	v_lshl_add_u64 v[48:49], s[0:1], 0, v[40:41]
	v_lshl_add_u64 v[162:163], s[0:1], 0, v[42:43]
	v_lshl_add_u64 v[164:165], s[0:1], 0, v[44:45]
	v_lshl_add_u64 v[166:167], s[0:1], 0, v[46:47]
	global_load_dwordx2 v[56:57], v[78:79], off
	global_load_dwordx2 v[52:53], v[48:49], off
	global_load_dwordx2 v[54:55], v[48:49], off offset:4
	global_load_dwordx2 v[64:65], v[78:79], off offset:512
	global_load_dwordx2 v[62:63], v[162:163], off
	global_load_dwordx2 v[66:67], v[162:163], off offset:4
	global_load_dwordx2 v[76:77], v[78:79], off offset:1024
	global_load_dwordx2 v[72:73], v[164:165], off
	global_load_dwordx2 v[74:75], v[164:165], off offset:4
	global_load_dwordx2 v[84:85], v[78:79], off offset:1536
	global_load_dwordx2 v[82:83], v[166:167], off
	global_load_dwordx2 v[86:87], v[166:167], off offset:4
	s_mov_b32 s14, 0xff00
	s_waitcnt vmcnt(10)
	v_lshrrev_b32_e32 v53, 8, v53
	s_waitcnt vmcnt(9)
	v_lshlrev_b32_e32 v51, 24, v55
	v_lshlrev_b32_e32 v54, 16, v54
	v_and_b32_e32 v53, 0xffff00, v53
	v_and_b32_sdwa v58, v52, s14 dst_sel:DWORD dst_unused:UNUSED_PAD src0_sel:WORD_1 src1_sel:DWORD
	v_lshlrev_b32_e32 v50, 8, v52
	v_or_b32_e32 v52, v51, v53
	v_or_b32_e32 v51, v54, v58
	v_and_b32_e32 v53, 0xffffff00, v55
	v_lshlrev_b32_e32 v54, 16, v56
	v_and_b32_e32 v55, 0xffff0000, v56
	v_lshlrev_b32_e32 v56, 16, v57
	v_and_b32_e32 v57, 0xffff0000, v57
	v_mul_f32_e32 v58, v57, v57
	v_pk_fma_f32 v[90:91], v[56:57], v[56:57], v[58:59] op_sel_hi:[1,1,0]
	v_lshl_add_u64 v[58:59], s[0:1], 0, v[42:43]
	v_mov_b32_e32 v98, v90
	s_waitcnt vmcnt(7)
	v_lshrrev_b32_e32 v63, 8, v63
	s_waitcnt vmcnt(6)
	v_lshlrev_b32_e32 v61, 24, v67
	v_lshlrev_b32_e32 v66, 16, v66
	v_and_b32_e32 v63, 0xffff00, v63
	v_and_b32_sdwa v68, v62, s14 dst_sel:DWORD dst_unused:UNUSED_PAD src0_sel:WORD_1 src1_sel:DWORD
	v_lshlrev_b32_e32 v60, 8, v62
	v_or_b32_e32 v62, v61, v63
	v_or_b32_e32 v61, v66, v68
	v_and_b32_e32 v63, 0xffffff00, v67
	v_lshlrev_b32_e32 v67, 16, v65
	v_lshlrev_b32_e32 v66, 16, v64
	v_and_b32_e32 v65, 0xffff0000, v65
	v_and_b32_e32 v64, 0xffff0000, v64
	v_pk_mul_f32 v[68:69], v[64:65], v[64:65]
	s_nop 0
	v_pk_fma_f32 v[94:95], v[66:67], v[66:67], v[68:69]
	v_lshl_add_u64 v[68:69], s[0:1], 0, v[44:45]
	v_lshl_add_u64 v[78:79], s[0:1], 0, v[46:47]
	v_pk_add_f32 v[94:95], v[94:95], v[94:95] op_sel:[0,1] op_sel_hi:[1,0]
	s_waitcnt vmcnt(4)
	v_lshrrev_b32_e32 v73, 8, v73
	s_waitcnt vmcnt(3)
	v_lshlrev_b32_e32 v71, 24, v75
	v_lshlrev_b32_e32 v74, 16, v74
	s_waitcnt vmcnt(1)
	v_lshrrev_b32_e32 v83, 8, v83
	v_and_b32_e32 v73, 0xffff00, v73
	v_and_b32_sdwa v80, v72, s14 dst_sel:DWORD dst_unused:UNUSED_PAD src0_sel:WORD_1 src1_sel:DWORD
	s_waitcnt vmcnt(0)
	v_lshlrev_b32_e32 v81, 24, v87
	v_lshlrev_b32_e32 v86, 16, v86
	v_and_b32_e32 v83, 0xffff00, v83
	v_and_b32_sdwa v88, v82, s14 dst_sel:DWORD dst_unused:UNUSED_PAD src0_sel:WORD_1 src1_sel:DWORD
	v_lshlrev_b32_e32 v70, 8, v72
	v_or_b32_e32 v72, v71, v73
	v_or_b32_e32 v71, v74, v80
	v_lshlrev_b32_e32 v80, 8, v82
	v_or_b32_e32 v82, v81, v83
	v_or_b32_e32 v81, v86, v88
	v_and_b32_e32 v83, 0xffffff00, v87
	v_and_b32_e32 v87, 0xffff0000, v84
	v_mul_f32_e32 v86, v55, v55
	v_lshlrev_b32_e32 v89, 16, v84
	v_pk_fma_f32 v[96:97], v[54:55], v[54:55], v[86:87] op_sel_hi:[1,1,0]
	v_mov_b32_e32 v99, v89
	v_mov_b32_e32 v88, v96
	v_and_b32_e32 v73, 0xffffff00, v75
	v_and_b32_e32 v75, 0xffff0000, v76
	v_mul_f32_e32 v93, v87, v87
	v_pk_add_f32 v[90:91], v[96:97], v[90:91]
	v_pk_mul_f32 v[96:97], v[88:89], v[98:99]
	v_lshlrev_b32_e32 v74, 16, v76
	v_lshlrev_b32_e32 v76, 16, v77
	v_and_b32_e32 v77, 0xffff0000, v77
	v_mov_b32_e32 v91, v97
	v_mov_b32_e32 v95, v93
	v_mul_f32_e32 v86, v75, v75
	v_lshlrev_b32_e32 v84, 16, v85
	v_and_b32_e32 v85, 0xffff0000, v85
	v_pk_add_f32 v[90:91], v[90:91], v[94:95]
	v_pk_fma_f32 v[94:95], v[74:75], v[74:75], v[86:87] op_sel_hi:[1,1,0]
	v_mul_f32_e32 v86, v77, v77
	v_mul_f32_e32 v100, v84, v84
	v_mul_f32_e32 v101, v85, v85
	v_pk_fma_f32 v[96:97], v[76:77], v[76:77], v[86:87] op_sel_hi:[1,1,0]
	v_mov_b32_e32 v95, v100
	v_mov_b32_e32 v97, v101
	v_pk_add_f32 v[94:95], v[94:95], v[96:97]
	v_and_b32_e32 v88, 64, v230
	v_pk_add_f32 v[90:91], v[90:91], v[94:95]
	v_add_u32_e32 v95, 64, v88
	v_add_f32_e32 v86, v90, v91
	s_mov_b32 s14, 0xf800000
	s_nop 1
	v_add_f32_dpp v86, v86, v86 quad_perm:[1,0,3,2] row_mask:0xf bank_mask:0xf
	s_nop 1
	v_add_f32_dpp v86, v86, v86 quad_perm:[2,3,0,1] row_mask:0xf bank_mask:0xf
	s_nop 1
	v_add_f32_dpp v86, v86, v86 row_half_mirror row_mask:0xf bank_mask:0xf
	s_nop 1
	v_add_f32_dpp v86, v86, v86 row_mirror row_mask:0xf bank_mask:0xf
	v_xor_b32_e32 v94, 16, v230
	v_cmp_lt_i32_e32 vcc, v94, v95
	s_nop 1
	v_cndmask_b32_e32 v94, v230, v94, vcc
	v_lshlrev_b32_e32 v94, 2, v94
	ds_bpermute_b32 v96, v94, v86
	s_waitcnt lgkmcnt(0)
	v_add_f32_e32 v86, v86, v96
	v_xor_b32_e32 v96, 32, v230
	v_cmp_lt_i32_e32 vcc, v96, v95
	s_nop 1
	v_cndmask_b32_e32 v95, v230, v96, vcc
	v_lshlrev_b32_e32 v95, 2, v95
	ds_bpermute_b32 v96, v95, v86
	s_waitcnt lgkmcnt(0)
; __device__ __forceinline__ void ew_phase(const Frame& F, const bf16_t* f, const float* gpost, float alpha, const float* hin, float* hout, const float* gpre, bf16_t* xn, ...
;     ...
;         const float rstd = alpha / sqrtf(wave_sum(s) * (1.f / DM) + RMS_EPS);
;         float s2 = 0.f; f32x4* ho = (f32x4*)(hout + (size_t)m * DM) + F.lane;
; #pragma unroll
;         for (int j = 0; j < 4; ++j) { hv[j] = hv[j] + fv[j] * rstd * gp[j]; if (out24) store24(h24 + (size_t)m * (DM * 3), F.lane + 64 * j, hv[j]); else ho[64 * j] = hv[j]; s2 += (hv[j].x * hv[j].x + hv[j].y * hv[j].y) + (hv[j].z * hv[j].z + hv[j].w * hv[j].w); }
	v_add_f32_e32 v86, v86, v96
	v_fmamk_f32 v86, v86, 0x3a800000, v225
	v_cmp_gt_f32_e32 vcc, s14, v86
	v_mul_f32_e32 v96, 0x4f800000, v86
	s_nop 0
	v_cndmask_b32_e32 v86, v86, v96, vcc
	v_sqrt_f32_e32 v96, v86
	s_nop 0
	v_add_u32_e32 v97, -1, v96
	v_fma_f32 v98, -v97, v96, v86
	v_cmp_ge_f32_e64 s[0:1], 0, v98
	v_add_u32_e32 v98, 1, v96
	s_nop 0
	v_cndmask_b32_e64 v97, v96, v97, s[0:1]
	v_fma_f32 v96, -v98, v96, v86
	v_cmp_lt_f32_e64 s[0:1], 0, v96
	s_nop 1
	v_cndmask_b32_e64 v96, v97, v98, s[0:1]
	v_mul_f32_e32 v97, 0x37800000, v96
	v_cndmask_b32_e32 v96, v96, v97, vcc
	v_cmp_class_f32_e32 vcc, v86, v226
	s_nop 1
	v_cndmask_b32_e32 v86, v96, v86, vcc
	v_div_scale_f32 v96, s[0:1], v86, v86, 1.0
	v_rcp_f32_e32 v97, v96
	s_mov_b32 s0, 0x7060503
	v_fma_f32 v98, -v96, v97, 1.0
	v_fmac_f32_e32 v97, v98, v97
	v_div_scale_f32 v98, vcc, 1.0, v86, 1.0
	v_mul_f32_e32 v99, v98, v97
	v_fma_f32 v100, -v96, v99, v98
	v_fmac_f32_e32 v99, v100, v97
	v_fma_f32 v96, -v96, v99, v98
	v_div_fmas_f32 v96, v96, v97, v99
	v_div_fixup_f32 v96, v96, v86, 1.0
	v_pk_mul_f32 v[54:55], v[96:97], v[54:55] op_sel_hi:[0,1]
	v_pk_mul_f32 v[56:57], v[96:97], v[56:57] op_sel_hi:[0,1]
	v_pk_fma_f32 v[52:53], v[4:5], v[56:57], v[52:53]
	v_pk_fma_f32 v[50:51], v[2:3], v[54:55], v[50:51]
	v_bfe_u32 v57, v52, 8, 1
	v_bfe_u32 v55, v51, 8, 1
	v_bfe_u32 v54, v50, 8, 1
	v_add3_u32 v55, v51, v55, s13
	v_add3_u32 v57, v52, v57, s13
	v_bfe_u32 v97, v53, 8, 1
	v_add3_u32 v54, v50, v54, s13
	v_lshrrev_b32_e32 v56, 8, v55
	v_lshrrev_b32_e32 v86, 8, v57
	v_add3_u32 v97, v53, v97, s13
	v_alignbit_b32 v54, v56, v54, 8
	v_alignbit_b32 v55, v86, v55, 16
	v_perm_b32 v56, v97, v57, s0
	global_store_dwordx3 v[48:49], v[54:56], off nt
	v_mov_b32_e32 v48, v66
	v_mov_b32_e32 v49, v64
	v_mov_b32_e32 v64, v67
	v_pk_mul_f32 v[54:55], v[96:97], v[48:49] op_sel_hi:[0,1]
	v_pk_mul_f32 v[48:49], v[96:97], v[64:65] op_sel_hi:[0,1]
	v_pk_fma_f32 v[48:49], v[16:17], v[48:49], v[62:63]
	v_pk_fma_f32 v[54:55], v[14:15], v[54:55], v[60:61]
	v_bfe_u32 v61, v48, 8, 1
	v_bfe_u32 v57, v55, 8, 1
	v_bfe_u32 v56, v54, 8, 1
	v_add3_u32 v57, v55, v57, s13
	v_add3_u32 v62, v48, v61, s13
	v_bfe_u32 v63, v49, 8, 1
	v_add3_u32 v56, v54, v56, s13
	v_lshrrev_b32_e32 v60, 8, v57
	v_lshrrev_b32_e32 v61, 8, v62
	v_add3_u32 v63, v49, v63, s13
	v_alignbit_b32 v60, v60, v56, 8
	v_alignbit_b32 v61, v61, v57, 16
	v_perm_b32 v62, v63, v62, s0
	global_store_dwordx3 v[58:59], v[60:62], off nt
	v_pk_mul_f32 v[58:59], v[96:97], v[74:75] op_sel_hi:[0,1]
	v_pk_mul_f32 v[56:57], v[96:97], v[76:77] op_sel_hi:[0,1]
	v_pk_fma_f32 v[56:57], v[20:21], v[56:57], v[72:73]
	v_pk_fma_f32 v[58:59], v[18:19], v[58:59], v[70:71]
	v_bfe_u32 v63, v56, 8, 1
	v_bfe_u32 v61, v59, 8, 1
	v_bfe_u32 v60, v58, 8, 1
	v_add3_u32 v61, v59, v61, s13
	v_add3_u32 v63, v56, v63, s13
	v_bfe_u32 v65, v57, 8, 1
	v_add3_u32 v60, v58, v60, s13
	v_lshrrev_b32_e32 v62, 8, v61
	v_lshrrev_b32_e32 v64, 8, v63
	v_add3_u32 v65, v57, v65, s13
	v_alignbit_b32 v60, v62, v60, 8
	v_alignbit_b32 v61, v64, v61, 16
	v_perm_b32 v62, v65, v63, s0
	v_mov_b32_e32 v86, v89
	global_store_dwordx3 v[68:69], v[60:62], off nt
	s_and_b64 vcc, exec, s[40:41]
	s_nop 0
	v_pk_mul_f32 v[62:63], v[86:87], v[96:97] op_sel_hi:[1,0]
	v_pk_mul_f32 v[60:61], v[84:85], v[96:97] op_sel_hi:[1,0]
	v_pk_fma_f32 v[62:63], v[30:31], v[62:63], v[80:81]
	v_pk_fma_f32 v[60:61], v[32:33], v[60:61], v[82:83]
	v_bfe_u32 v65, v63, 8, 1
	v_bfe_u32 v67, v60, 8, 1
	v_bfe_u32 v64, v62, 8, 1
	v_add3_u32 v65, v63, v65, s13
	v_add3_u32 v67, v60, v67, s13
	v_bfe_u32 v69, v61, 8, 1
	v_add3_u32 v64, v62, v64, s13
	v_lshrrev_b32_e32 v66, 8, v65
	v_lshrrev_b32_e32 v68, 8, v67
	v_add3_u32 v69, v61, v69, s13
	v_alignbit_b32 v64, v66, v64, 8
	v_alignbit_b32 v65, v68, v65, 16
	v_perm_b32 v66, v69, v67, s0
	global_store_dwordx3 v[78:79], v[64:66], off nt
	s_cbranch_vccnz .LBB0_810
; __device__ __forceinline__ unsigned cvt_pk_bf16(float lo, float hi) { f32x2 v = {lo, hi}; bf16x2_t b = __builtin_convertvector(v, bf16x2_t); return __builtin_bit_cast(unsigned, b); }
; __device__ __forceinline__ void ew_phase(const Frame& F, const bf16_t* f, const float* gpost, float alpha, const float* hin, float* hout, const float* gpre, bf16_t* xn, ...
;     ...
;         if (gpre) {
;             const float r2 = 1.0f / sqrtf(wave_sum(s2) * (1.f / DM) + RMS_EPS);
;             u32x2* o8 = (u32x2*)(xn + (size_t)m * DM) + F.lane;
; #pragma unroll
;             for (int j = 0; j < 4; ++j) { hv[j] = hv[j] * r2 * gq[j]; u32x2 w; w.x = cvt_pk_bf16(hv[j].x, hv[j].y); w.y = cvt_pk_bf16(hv[j].z, hv[j].w); o8[64 * j] = w; }
	s_nop 0
	v_pk_mul_f32 v[64:65], v[52:53], v[52:53]
	v_pk_mul_f32 v[66:67], v[50:51], v[50:51]
	v_mov_b32_e32 v69, v65
	v_mov_b32_e32 v68, v66
	v_pk_mov_b32 v[64:65], v[66:67], v[64:65] op_sel:[1,0]
	v_pk_mul_f32 v[66:67], v[48:49], v[48:49]
	v_pk_add_f32 v[64:65], v[68:69], v[64:65]
	v_pk_mul_f32 v[68:69], v[54:55], v[54:55]
	v_pk_add_f32 v[64:65], v[64:65], v[64:65] op_sel_hi:[0,1]
	v_mov_b32_e32 v70, v68
	v_mov_b32_e32 v71, v67
	v_pk_mov_b32 v[66:67], v[68:69], v[66:67] op_sel:[1,0]
	v_mul_f32_e32 v64, v58, v58
	v_pk_add_f32 v[66:67], v[70:71], v[66:67]
	v_pk_fma_f32 v[68:69], v[58:59], v[58:59], v[64:65] op_sel_hi:[1,1,0]
	v_mul_f32_e32 v64, v56, v56
	v_pk_add_f32 v[66:67], v[66:67], v[66:67] op_sel_hi:[0,1]
	v_pk_fma_f32 v[70:71], v[56:57], v[56:57], v[64:65] op_sel_hi:[1,1,0]
	v_mul_f32_e32 v68, v62, v62
	v_mul_f32_e32 v70, v63, v63
	v_mul_f32_e32 v64, v61, v61
	v_mul_f32_e32 v66, v60, v60
	v_pk_add_f32 v[68:69], v[68:69], v[70:71]
	v_pk_add_f32 v[64:65], v[64:65], v[66:67]
	s_lshl_b64 s[8:9], s[8:9], 10
	v_pk_add_f32 v[64:65], v[68:69], v[64:65]
	s_nop 0
	v_add_f32_e32 v64, v64, v65
	s_nop 1
	v_add_f32_dpp v64, v64, v64 quad_perm:[1,0,3,2] row_mask:0xf bank_mask:0xf
	s_nop 1
	v_add_f32_dpp v64, v64, v64 quad_perm:[2,3,0,1] row_mask:0xf bank_mask:0xf
	s_nop 1
	v_add_f32_dpp v64, v64, v64 row_half_mirror row_mask:0xf bank_mask:0xf
	s_nop 1
	v_add_f32_dpp v64, v64, v64 row_mirror row_mask:0xf bank_mask:0xf
	ds_bpermute_b32 v65, v94, v64
	s_waitcnt lgkmcnt(0)
	v_add_f32_e32 v64, v64, v65
	ds_bpermute_b32 v65, v95, v64
	s_waitcnt lgkmcnt(0)
	v_add_f32_e32 v64, v64, v65
	v_fmamk_f32 v64, v64, 0x3a800000, v225
	v_mul_f32_e32 v65, 0x4f800000, v64
	v_cmp_gt_f32_e32 vcc, s14, v64
	s_nop 1
	v_cndmask_b32_e32 v64, v64, v65, vcc
	v_sqrt_f32_e32 v65, v64
	s_nop 0
	v_add_u32_e32 v66, -1, v65
	v_add_u32_e32 v67, 1, v65
	v_fma_f32 v68, -v66, v65, v64
	v_fma_f32 v69, -v67, v65, v64
	v_cmp_ge_f32_e64 s[0:1], 0, v68
	s_nop 1
	v_cndmask_b32_e64 v65, v65, v66, s[0:1]
	v_cmp_lt_f32_e64 s[0:1], 0, v69
	s_nop 1
	v_cndmask_b32_e64 v65, v65, v67, s[0:1]
	v_mul_f32_e32 v66, 0x37800000, v65
	v_cndmask_b32_e32 v65, v65, v66, vcc
	v_cmp_class_f32_e32 vcc, v64, v226
	s_nop 1
	v_cndmask_b32_e32 v66, v65, v64, vcc
	v_div_scale_f32 v67, s[0:1], v66, v66, 1.0
	v_rcp_f32_e32 v68, v67
	v_div_scale_f32 v69, vcc, 1.0, v66, 1.0
	v_lshl_add_u64 v[64:65], s[8:9], 1, v[38:39]
	v_fma_f32 v70, -v67, v68, 1.0
	v_fmac_f32_e32 v68, v70, v68
	v_mul_f32_e32 v70, v69, v68
	v_fma_f32 v71, -v67, v70, v69
	v_fmac_f32_e32 v70, v71, v68
	v_fma_f32 v67, -v67, v70, v69
	v_div_fmas_f32 v67, v67, v68, v70
	v_div_fixup_f32 v66, v67, v66, 1.0
	v_pk_mul_f32 v[50:51], v[50:51], v[66:67] op_sel_hi:[1,0]
	v_pk_mul_f32 v[52:53], v[52:53], v[66:67] op_sel_hi:[1,0]
	v_pk_mul_f32 v[50:51], v[10:11], v[50:51]
	v_pk_mul_f32 v[52:53], v[12:13], v[52:53]
	v_cvt_pk_bf16_f32 v50, v50, v51
	v_cvt_pk_bf16_f32 v51, v52, v53
	global_store_dwordx2 v[64:65], v[50:51], off nt
	v_pk_mul_f32 v[50:51], v[54:55], v[66:67] op_sel_hi:[1,0]
	v_pk_mul_f32 v[48:49], v[48:49], v[66:67] op_sel_hi:[1,0]
	v_pk_mul_f32 v[50:51], v[6:7], v[50:51]
	v_pk_mul_f32 v[48:49], v[8:9], v[48:49]
	v_cvt_pk_bf16_f32 v50, v50, v51
	v_cvt_pk_bf16_f32 v51, v48, v49
	global_store_dwordx2 v[64:65], v[50:51], off offset:512 nt
	v_pk_mul_f32 v[48:49], v[58:59], v[66:67] op_sel_hi:[1,0]
	v_pk_mul_f32 v[50:51], v[56:57], v[66:67] op_sel_hi:[1,0]
	v_pk_mul_f32 v[48:49], v[26:27], v[48:49]
	v_pk_mul_f32 v[50:51], v[28:29], v[50:51]
	v_cvt_pk_bf16_f32 v48, v48, v49
	v_cvt_pk_bf16_f32 v49, v50, v51
	global_store_dwordx2 v[64:65], v[48:49], off offset:1024 nt
	v_pk_mul_f32 v[48:49], v[62:63], v[66:67] op_sel_hi:[1,0]
	v_pk_mul_f32 v[50:51], v[60:61], v[66:67] op_sel_hi:[1,0]
	v_pk_mul_f32 v[48:49], v[22:23], v[48:49]
	v_pk_mul_f32 v[50:51], v[24:25], v[50:51]
	v_cvt_pk_bf16_f32 v48, v48, v49
	v_cvt_pk_bf16_f32 v49, v50, v51
	global_store_dwordx2 v[64:65], v[48:49], off offset:1536 nt
	s_branch .LBB0_810

; __device__ __forceinline__ float bf_lo(unsigned w) { return __uint_as_float(w << 16); }
; __device__ __forceinline__ float bf_hi(unsigned w) { return __uint_as_float(w & 0xffff0000u); }
; __device__ __forceinline__ void ew_phase(const Frame& F, const bf16_t* f, const float* gpost, float alpha, const float* hin, float* hout, const float* gpre, bf16_t* xn, ...
;     ...
;         const int m = prow0 >= 0 ? prow0 + F.wave * 8 + it_ : F.gw + it_ * F.NGW; if (m >= T) break;
;         const u32x2* fr = (const u32x2*)(f + (size_t)m * DM) + F.lane; const f32x4* hr = (const f32x4*)(hin + (size_t)m * DM) + F.lane;
;         f32x4 fv[4], hv[4]; float s = 0.f;
; #pragma unroll
;         for (int j = 0; j < 4; ++j) { const u32x2 w = fr[64 * j]; hv[j] = in24 ? load24(h24 + (size_t)m * (DM * 3), F.lane + 64 * j) : hr[64 * j]; fv[j] = (f32x4){bf_lo(w.x), bf_hi(w.x), bf_lo(w.y), bf_hi(w.y)};
;             s += (fv[j].x * fv[j].x + fv[j].y * fv[j].y) + (fv[j].z * fv[j].z + fv[j].w * fv[j].w); }
;         const float rstd = alpha / sqrtf(wave_sum(s) * (1.f / DM) + RMS_EPS);
.LBB0_905:
	v_readlane_b32 s0, v252, 11
	s_add_i32 s6, s2, s3
	v_readlane_b32 s1, v252, 12
	s_and_b64 s[0:1], s[0:1], exec
	s_cselect_b32 s8, s6, s12
	s_cmpk_gt_i32 s8, 0x3fff
	s_mov_b64 s[0:1], -1
	s_cbranch_scc1 .LBB0_904
	s_ashr_i32 s9, s8, 31
	s_lshl_b64 s[6:7], s[8:9], 11
	s_mul_i32 s0, s8, 0xc00
	s_mul_hi_i32 s1, s8, 0xc00
	s_add_u32 s0, s13, s0
	s_addc_u32 s1, s14, s1
	v_lshl_add_u64 v[68:69], v[44:45], 0, s[6:7]
	v_lshl_add_u64 v[48:49], s[0:1], 0, v[36:37]
	v_lshl_add_u64 v[58:59], s[0:1], 0, v[38:39]
	v_lshl_add_u64 v[162:163], s[0:1], 0, v[40:41]
	v_lshl_add_u64 v[164:165], s[0:1], 0, v[42:43]
	global_load_dwordx2 v[56:57], v[68:69], off
	global_load_dwordx2 v[52:53], v[48:49], off
	global_load_dwordx2 v[54:55], v[48:49], off offset:4
	global_load_dwordx2 v[64:65], v[68:69], off offset:512
	global_load_dwordx2 v[62:63], v[58:59], off
	global_load_dwordx2 v[66:67], v[58:59], off offset:4
	global_load_dwordx2 v[72:73], v[68:69], off offset:1024
	global_load_dwordx2 v[76:77], v[162:163], off
	global_load_dwordx2 v[78:79], v[162:163], off offset:4
	global_load_dwordx2 v[80:81], v[68:69], off offset:1536
	global_load_dwordx2 v[166:167], v[164:165], off
	global_load_dwordx2 v[82:83], v[164:165], off offset:4
	s_mov_b32 s8, 0xff00
	s_add_i32 s3, s3, 1
	s_addk_i32 s12, 0x800
	s_cmp_eq_u32 s3, 8
	s_waitcnt vmcnt(10)
	v_lshrrev_b32_e32 v51, 8, v53
	s_waitcnt vmcnt(9)
	v_lshlrev_b32_e32 v0, 24, v55
	v_lshlrev_b32_e32 v35, 16, v54
	v_and_b32_e32 v51, 0xffff00, v51
	v_and_b32_sdwa v53, v52, s8 dst_sel:DWORD dst_unused:UNUSED_PAD src0_sel:WORD_1 src1_sel:DWORD
	v_lshlrev_b32_e32 v50, 8, v52
	v_or_b32_e32 v52, v0, v51
	v_or_b32_e32 v51, v35, v53
	v_and_b32_e32 v53, 0xffffff00, v55
	v_lshlrev_b32_e32 v54, 16, v56
	v_and_b32_e32 v55, 0xffff0000, v56
	v_lshlrev_b32_e32 v56, 16, v57
	v_and_b32_e32 v57, 0xffff0000, v57
	v_mul_f32_e32 v0, v57, v57
	s_waitcnt vmcnt(7)
	v_lshrrev_b32_e32 v61, 8, v63
	v_pk_fma_f32 v[90:91], v[56:57], v[56:57], v[0:1] op_sel_hi:[1,1,0]
	s_waitcnt vmcnt(6)
	v_lshlrev_b32_e32 v0, 24, v67
	v_lshlrev_b32_e32 v35, 16, v66
	v_and_b32_e32 v61, 0xffff00, v61
	v_and_b32_sdwa v63, v62, s8 dst_sel:DWORD dst_unused:UNUSED_PAD src0_sel:WORD_1 src1_sel:DWORD
	v_lshlrev_b32_e32 v60, 8, v62
	v_or_b32_e32 v62, v0, v61
	v_or_b32_e32 v61, v35, v63
	v_and_b32_e32 v63, 0xffffff00, v67
	v_lshlrev_b32_e32 v67, 16, v65
	v_lshlrev_b32_e32 v66, 16, v64
	v_and_b32_e32 v65, 0xffff0000, v65
	v_and_b32_e32 v64, 0xffff0000, v64
	v_pk_mul_f32 v[70:71], v[64:65], v[64:65]
	s_waitcnt vmcnt(5)
	v_lshlrev_b32_e32 v88, 16, v73
	v_pk_fma_f32 v[96:97], v[66:67], v[66:67], v[70:71]
	v_lshl_add_u64 v[70:71], s[0:1], 0, v[40:41]
	v_lshl_add_u64 v[68:69], s[0:1], 0, v[42:43]
	v_and_b32_e32 v89, 0xffff0000, v73
	v_lshlrev_b32_e32 v86, 16, v72
	v_and_b32_e32 v87, 0xffff0000, v72
	v_mov_b32_e32 v100, v90
	v_pk_add_f32 v[96:97], v[96:97], v[96:97] op_sel:[0,1] op_sel_hi:[1,0]
	s_waitcnt vmcnt(4)
	v_lshrrev_b32_e32 v75, 8, v77
	v_lshlrev_b32_e32 v74, 8, v76
	s_waitcnt vmcnt(3)
	v_lshlrev_b32_e32 v0, 24, v79
	v_lshlrev_b32_e32 v35, 16, v78
	v_and_b32_e32 v75, 0xffff00, v75
	v_and_b32_sdwa v76, v76, s8 dst_sel:DWORD dst_unused:UNUSED_PAD src0_sel:WORD_1 src1_sel:DWORD
	v_or_b32_e32 v78, v0, v75
	v_or_b32_e32 v75, v35, v76
	s_waitcnt vmcnt(2)
	v_lshlrev_b32_e32 v85, 16, v80
	v_mov_b32_e32 v101, v85
	v_and_b32_e32 v79, 0xffffff00, v79
	s_waitcnt vmcnt(1)
	v_lshrrev_b32_e32 v73, 8, v167
	s_waitcnt vmcnt(0)
	v_lshlrev_b32_e32 v0, 24, v83
	v_and_b32_e32 v73, 0xffff00, v73
	v_lshlrev_b32_e32 v72, 8, v166
	v_and_b32_sdwa v77, v166, s8 dst_sel:DWORD dst_unused:UNUSED_PAD src0_sel:WORD_1 src1_sel:DWORD
	v_or_b32_e32 v76, v0, v73
	v_mul_f32_e32 v0, v55, v55
	v_lshlrev_b32_e32 v35, 16, v82
	v_pk_fma_f32 v[98:99], v[54:55], v[54:55], v[0:1] op_sel_hi:[1,1,0]
	v_or_b32_e32 v73, v35, v77
	v_and_b32_e32 v77, 0xffffff00, v83
	v_and_b32_e32 v83, 0xffff0000, v80
	v_mov_b32_e32 v84, v98
	v_mul_f32_e32 v35, v83, v83
	v_pk_add_f32 v[90:91], v[98:99], v[90:91]
	v_pk_mul_f32 v[98:99], v[84:85], v[100:101]
	v_mov_b32_e32 v97, v35
	v_mov_b32_e32 v91, v99
	v_mul_f32_e32 v0, v87, v87
	v_lshlrev_b32_e32 v80, 16, v81
	v_and_b32_e32 v81, 0xffff0000, v81
	v_pk_add_f32 v[90:91], v[90:91], v[96:97]
	v_pk_fma_f32 v[96:97], v[86:87], v[86:87], v[0:1] op_sel_hi:[1,1,0]
	v_mul_f32_e32 v0, v89, v89
	v_mul_f32_e32 v82, v80, v80
	v_mul_f32_e32 v102, v81, v81
	v_pk_fma_f32 v[98:99], v[88:89], v[88:89], v[0:1] op_sel_hi:[1,1,0]
	v_and_b32_e32 v0, 64, v230
	v_mov_b32_e32 v97, v82
	v_mov_b32_e32 v99, v102
	v_add_u32_e32 v82, 64, v0
	v_xor_b32_e32 v0, 1, v230
	v_pk_add_f32 v[96:97], v[96:97], v[98:99]
	v_cmp_lt_i32_e32 vcc, v0, v82
	v_pk_add_f32 v[90:91], v[90:91], v[96:97]
	s_nop 0
	v_cndmask_b32_e32 v0, v230, v0, vcc
	v_add_f32_e32 v35, v90, v91
	v_lshlrev_b32_e32 v0, 2, v0
	s_nop 1
	v_add_f32_dpp v84, v35, v35 quad_perm:[1,0,3,2] row_mask:0xf bank_mask:0xf
	v_xor_b32_e32 v35, 2, v230
	v_cmp_lt_i32_e32 vcc, v35, v82
	s_nop 1
	v_cndmask_b32_e32 v35, v230, v35, vcc
	v_lshlrev_b32_e32 v35, 2, v35
	s_nop 1
	v_add_f32_dpp v90, v84, v84 quad_perm:[2,3,0,1] row_mask:0xf bank_mask:0xf
	v_xor_b32_e32 v84, 4, v230
	v_cmp_lt_i32_e32 vcc, v84, v82
	s_nop 1
	v_cndmask_b32_e32 v84, v230, v84, vcc
	v_lshlrev_b32_e32 v84, 2, v84
	s_nop 1
	v_add_f32_dpp v91, v90, v90 row_half_mirror row_mask:0xf bank_mask:0xf
	v_xor_b32_e32 v90, 8, v230
	v_cmp_lt_i32_e32 vcc, v90, v82
	s_nop 1
	v_cndmask_b32_e32 v90, v230, v90, vcc
	v_lshlrev_b32_e32 v90, 2, v90
	s_nop 1
	v_add_f32_dpp v91, v91, v91 row_mirror row_mask:0xf bank_mask:0xf
	v_xor_b32_e32 v96, 16, v230
	v_cmp_lt_i32_e32 vcc, v96, v82
	s_nop 1
	v_cndmask_b32_e32 v96, v230, v96, vcc
	v_lshlrev_b32_e32 v97, 2, v96
	ds_bpermute_b32 v96, v97, v91
	s_waitcnt lgkmcnt(0)
; __device__ __forceinline__ void ew_phase(const Frame& F, const bf16_t* f, const float* gpost, float alpha, const float* hin, float* hout, const float* gpre, bf16_t* xn, ...
;     ...
;         const float rstd = alpha / sqrtf(wave_sum(s) * (1.f / DM) + RMS_EPS);
;         float s2 = 0.f; f32x4* ho = (f32x4*)(hout + (size_t)m * DM) + F.lane;
; #pragma unroll
;         for (int j = 0; j < 4; ++j) { hv[j] = hv[j] + fv[j] * rstd * gp[j]; if (out24) store24(h24 + (size_t)m * (DM * 3), F.lane + 64 * j, hv[j]); else ho[64 * j] = hv[j]; s2 += (hv[j].x * hv[j].x + hv[j].y * hv[j].y) + (hv[j].z * hv[j].z + hv[j].w * hv[j].w); }
;         if (gpre) {
;             const float r2 = 1.0f / sqrtf(wave_sum(s2) * (1.f / DM) + RMS_EPS);
	v_add_f32_e32 v91, v91, v96
	v_xor_b32_e32 v96, 32, v230
	v_cmp_lt_i32_e32 vcc, v96, v82
	s_nop 1
	v_cndmask_b32_e32 v82, v230, v96, vcc
	v_lshlrev_b32_e32 v100, 2, v82
	ds_bpermute_b32 v82, v100, v91
	s_waitcnt lgkmcnt(0)
	v_add_f32_e32 v82, v91, v82
	v_fmamk_f32 v82, v82, 0x3a800000, v225
	v_cmp_gt_f32_e32 vcc, s18, v82
	v_mul_f32_e32 v91, 0x4f800000, v82
	s_nop 0
	v_cndmask_b32_e32 v82, v82, v91, vcc
	v_sqrt_f32_e32 v91, v82
	s_nop 0
	v_add_u32_e32 v96, -1, v91
	v_fma_f32 v98, -v96, v91, v82
	v_cmp_ge_f32_e64 s[0:1], 0, v98
	v_add_u32_e32 v98, 1, v91
	s_nop 0
	v_cndmask_b32_e64 v96, v91, v96, s[0:1]
	v_fma_f32 v91, -v98, v91, v82
	v_cmp_lt_f32_e64 s[0:1], 0, v91
	s_nop 1
	v_cndmask_b32_e64 v91, v96, v98, s[0:1]
	v_mul_f32_e32 v96, 0x37800000, v91
	v_cndmask_b32_e32 v91, v91, v96, vcc
	v_cmp_class_f32_e32 vcc, v82, v226
	s_nop 1
	v_cndmask_b32_e32 v82, v91, v82, vcc
	v_div_scale_f32 v91, s[0:1], v82, v82, 0.5
	v_rcp_f32_e32 v96, v91
	s_mov_b32 s0, 0x7060503
	v_fma_f32 v98, -v91, v96, 1.0
	v_fmac_f32_e32 v96, v98, v96
	v_div_scale_f32 v98, vcc, 0.5, v82, 0.5
	v_mul_f32_e32 v99, v98, v96
	v_fma_f32 v101, -v91, v99, v98
	v_fmac_f32_e32 v99, v101, v96
	v_fma_f32 v91, -v91, v99, v98
	v_div_fmas_f32 v91, v91, v96, v99
	v_div_fixup_f32 v96, v91, v82, 0.5
	v_pk_mul_f32 v[54:55], v[96:97], v[54:55] op_sel_hi:[0,1]
	v_pk_mul_f32 v[56:57], v[96:97], v[56:57] op_sel_hi:[0,1]
	v_pk_fma_f32 v[52:53], v[4:5], v[56:57], v[52:53]
	v_pk_fma_f32 v[50:51], v[2:3], v[54:55], v[50:51]
	v_bfe_u32 v57, v52, 8, 1
	v_bfe_u32 v55, v51, 8, 1
	v_bfe_u32 v54, v50, 8, 1
	v_add3_u32 v55, v51, v55, s15
	v_add3_u32 v57, v52, v57, s15
	v_bfe_u32 v91, v53, 8, 1
	v_add3_u32 v54, v50, v54, s15
	v_lshrrev_b32_e32 v56, 8, v55
	v_lshrrev_b32_e32 v82, 8, v57
	v_add3_u32 v91, v53, v91, s15
	v_alignbit_b32 v54, v56, v54, 8
	v_alignbit_b32 v55, v82, v55, 16
	v_perm_b32 v56, v91, v57, s0
	global_store_dwordx3 v[48:49], v[54:56], off nt
	v_pk_mul_f32 v[48:49], v[52:53], v[52:53]
	v_mov_b32_e32 v82, v85
	v_pk_mul_f32 v[54:55], v[50:51], v[50:51]
	s_nop 0
	v_pk_mov_b32 v[56:57], v[54:55], v[48:49] op_sel:[1,0]
	v_mov_b32_e32 v55, v49
	v_pk_add_f32 v[48:49], v[54:55], v[56:57]
	s_nop 0
	v_pk_add_f32 v[98:99], v[48:49], v[48:49] op_sel_hi:[0,1]
	v_mov_b32_e32 v48, v66
	v_mov_b32_e32 v49, v64
	v_mov_b32_e32 v64, v67
	v_pk_mul_f32 v[54:55], v[96:97], v[48:49] op_sel_hi:[0,1]
	v_pk_mul_f32 v[48:49], v[96:97], v[64:65] op_sel_hi:[0,1]
	v_pk_fma_f32 v[48:49], v[8:9], v[48:49], v[62:63]
	v_pk_fma_f32 v[54:55], v[6:7], v[54:55], v[60:61]
	v_bfe_u32 v61, v48, 8, 1
	v_bfe_u32 v57, v55, 8, 1
	v_bfe_u32 v56, v54, 8, 1
	v_add3_u32 v57, v55, v57, s15
	v_add3_u32 v62, v48, v61, s15
	v_bfe_u32 v63, v49, 8, 1
	v_add3_u32 v56, v54, v56, s15
	v_lshrrev_b32_e32 v60, 8, v57
	v_lshrrev_b32_e32 v61, 8, v62
	v_add3_u32 v63, v49, v63, s15
	v_alignbit_b32 v60, v60, v56, 8
	v_alignbit_b32 v61, v61, v57, 16
	v_perm_b32 v62, v63, v62, s0
	global_store_dwordx3 v[58:59], v[60:62], off nt
	v_pk_mul_f32 v[56:57], v[48:49], v[48:49]
	v_pk_mul_f32 v[58:59], v[54:55], v[54:55]
	s_nop 0
	v_pk_mov_b32 v[60:61], v[58:59], v[56:57] op_sel:[1,0]
	v_mov_b32_e32 v59, v57
	v_pk_add_f32 v[56:57], v[58:59], v[60:61]
	v_pk_mul_f32 v[58:59], v[96:97], v[86:87] op_sel_hi:[0,1]
	v_pk_add_f32 v[66:67], v[56:57], v[56:57] op_sel_hi:[0,1]
	v_pk_mul_f32 v[56:57], v[96:97], v[88:89] op_sel_hi:[0,1]
	v_pk_fma_f32 v[56:57], v[20:21], v[56:57], v[78:79]
	v_pk_fma_f32 v[58:59], v[18:19], v[58:59], v[74:75]
	v_bfe_u32 v63, v56, 8, 1
	v_bfe_u32 v61, v59, 8, 1
	v_bfe_u32 v60, v58, 8, 1
	v_add3_u32 v61, v59, v61, s15
	v_add3_u32 v63, v56, v63, s15
	v_bfe_u32 v65, v57, 8, 1
	v_add3_u32 v60, v58, v60, s15
	v_lshrrev_b32_e32 v62, 8, v61
	v_lshrrev_b32_e32 v64, 8, v63
	v_add3_u32 v65, v57, v65, s15
	v_alignbit_b32 v60, v62, v60, 8
	v_alignbit_b32 v61, v64, v61, 16
	v_perm_b32 v62, v65, v63, s0
	global_store_dwordx3 v[70:71], v[60:62], off nt
	s_nop 1
	v_mul_f32_e32 v60, v58, v58
	v_pk_fma_f32 v[70:71], v[58:59], v[58:59], v[60:61] op_sel_hi:[1,1,0]
	v_mul_f32_e32 v60, v56, v56
	v_pk_fma_f32 v[74:75], v[56:57], v[56:57], v[60:61] op_sel_hi:[1,1,0]
	v_pk_mul_f32 v[62:63], v[82:83], v[96:97] op_sel_hi:[1,0]
	v_pk_mul_f32 v[60:61], v[80:81], v[96:97] op_sel_hi:[1,0]
	v_pk_fma_f32 v[62:63], v[22:23], v[62:63], v[72:73]
	v_pk_fma_f32 v[60:61], v[24:25], v[60:61], v[76:77]
	v_bfe_u32 v65, v63, 8, 1
	v_bfe_u32 v70, v60, 8, 1
	v_bfe_u32 v64, v62, 8, 1
	v_add3_u32 v65, v63, v65, s15
	v_add3_u32 v70, v60, v70, s15
	v_bfe_u32 v73, v61, 8, 1
	v_add3_u32 v64, v62, v64, s15
	v_lshrrev_b32_e32 v66, 8, v65
	v_lshrrev_b32_e32 v72, 8, v70
	v_add3_u32 v73, v61, v73, s15
	v_alignbit_b32 v64, v66, v64, 8
	v_alignbit_b32 v65, v72, v65, 16
	v_perm_b32 v66, v73, v70, s0
	global_store_dwordx3 v[68:69], v[64:66], off nt
	v_mul_f32_e32 v70, v62, v62
	v_mul_f32_e32 v74, v63, v63
	v_mul_f32_e32 v98, v61, v61
	v_mul_f32_e32 v66, v60, v60
	v_pk_add_f32 v[64:65], v[70:71], v[74:75]
	v_pk_add_f32 v[66:67], v[98:99], v[66:67]
	s_nop 0
	v_pk_add_f32 v[64:65], v[64:65], v[66:67]
	s_nop 0
	v_add_f32_e32 v64, v64, v65
	s_nop 1
	v_add_f32_dpp v0, v64, v64 quad_perm:[1,0,3,2] row_mask:0xf bank_mask:0xf
	s_nop 1
	v_add_f32_dpp v0, v0, v0 quad_perm:[2,3,0,1] row_mask:0xf bank_mask:0xf
	s_nop 1
	v_add_f32_dpp v0, v0, v0 row_half_mirror row_mask:0xf bank_mask:0xf
	s_nop 1
	v_add_f32_dpp v0, v0, v0 row_mirror row_mask:0xf bank_mask:0xf
	ds_bpermute_b32 v35, v97, v0
	s_waitcnt lgkmcnt(0)
; __device__ __forceinline__ unsigned cvt_pk_bf16(float lo, float hi) { f32x2 v = {lo, hi}; bf16x2_t b = __builtin_convertvector(v, bf16x2_t); return __builtin_bit_cast(unsigned, b); }
; __device__ __forceinline__ void ew_phase(const Frame& F, const bf16_t* f, const float* gpost, float alpha, const float* hin, float* hout, const float* gpre, bf16_t* xn, ...
;     ...
;             const float r2 = 1.0f / sqrtf(wave_sum(s2) * (1.f / DM) + RMS_EPS);
;             u32x2* o8 = (u32x2*)(xn + (size_t)m * DM) + F.lane;
; #pragma unroll
;             for (int j = 0; j < 4; ++j) { hv[j] = hv[j] * r2 * gq[j]; u32x2 w; w.x = cvt_pk_bf16(hv[j].x, hv[j].y); w.y = cvt_pk_bf16(hv[j].z, hv[j].w); o8[64 * j] = w; }
	v_add_f32_e32 v0, v0, v35
	ds_bpermute_b32 v35, v100, v0
	s_waitcnt lgkmcnt(0)
	v_add_f32_e32 v0, v0, v35
	v_fmamk_f32 v0, v0, 0x3a800000, v225
	v_cmp_gt_f32_e32 vcc, s18, v0
	v_mul_f32_e32 v35, 0x4f800000, v0
	s_nop 0
	v_cndmask_b32_e32 v0, v0, v35, vcc
	v_sqrt_f32_e32 v35, v0
	s_nop 0
	v_add_u32_e32 v64, -1, v35
	v_fma_f32 v65, -v64, v35, v0
	v_cmp_ge_f32_e64 s[0:1], 0, v65
	v_add_u32_e32 v65, 1, v35
	s_nop 0
	v_cndmask_b32_e64 v64, v35, v64, s[0:1]
	v_fma_f32 v35, -v65, v35, v0
	v_cmp_lt_f32_e64 s[0:1], 0, v35
	s_nop 1
	v_cndmask_b32_e64 v35, v64, v65, s[0:1]
	v_mul_f32_e32 v64, 0x37800000, v35
	v_cndmask_b32_e32 v35, v35, v64, vcc
	v_cmp_class_f32_e32 vcc, v0, v226
	s_nop 1
	v_cndmask_b32_e32 v0, v35, v0, vcc
	v_div_scale_f32 v35, s[0:1], v0, v0, 1.0
	v_rcp_f32_e32 v64, v35
	s_cselect_b64 s[0:1], -1, 0
	v_fma_f32 v65, -v35, v64, 1.0
	v_fmac_f32_e32 v64, v65, v64
	v_div_scale_f32 v65, vcc, 1.0, v0, 1.0
	v_mul_f32_e32 v66, v65, v64
	v_fma_f32 v67, -v35, v66, v65
	v_fmac_f32_e32 v66, v67, v64
	v_fma_f32 v35, -v35, v66, v65
	v_div_fmas_f32 v35, v35, v64, v66
	v_div_fixup_f32 v0, v35, v0, 1.0
	v_pk_mul_f32 v[50:51], v[50:51], v[0:1] op_sel_hi:[1,0]
	v_pk_mul_f32 v[52:53], v[52:53], v[0:1] op_sel_hi:[1,0]
	v_pk_mul_f32 v[50:51], v[10:11], v[50:51]
	v_pk_mul_f32 v[52:53], v[12:13], v[52:53]
	v_lshl_add_u64 v[64:65], v[46:47], 0, s[6:7]
	v_cvt_pk_bf16_f32 v50, v50, v51
	v_cvt_pk_bf16_f32 v51, v52, v53
	global_store_dwordx2 v[64:65], v[50:51], off nt
	v_pk_mul_f32 v[50:51], v[54:55], v[0:1] op_sel_hi:[1,0]
	v_pk_mul_f32 v[48:49], v[48:49], v[0:1] op_sel_hi:[1,0]
	v_pk_mul_f32 v[50:51], v[14:15], v[50:51]
	v_pk_mul_f32 v[48:49], v[16:17], v[48:49]
	v_cvt_pk_bf16_f32 v50, v50, v51
	v_cvt_pk_bf16_f32 v51, v48, v49
	global_store_dwordx2 v[64:65], v[50:51], off offset:512 nt
	v_pk_mul_f32 v[48:49], v[58:59], v[0:1] op_sel_hi:[1,0]
	v_pk_mul_f32 v[50:51], v[56:57], v[0:1] op_sel_hi:[1,0]
	v_pk_mul_f32 v[48:49], v[26:27], v[48:49]
	v_pk_mul_f32 v[50:51], v[28:29], v[50:51]
	v_cvt_pk_bf16_f32 v48, v48, v49
	v_cvt_pk_bf16_f32 v49, v50, v51
	global_store_dwordx2 v[64:65], v[48:49], off offset:1024 nt
	v_pk_mul_f32 v[48:49], v[62:63], v[0:1] op_sel_hi:[1,0]
	v_pk_mul_f32 v[50:51], v[60:61], v[0:1] op_sel_hi:[1,0]
	v_pk_mul_f32 v[48:49], v[30:31], v[48:49]
	v_pk_mul_f32 v[50:51], v[32:33], v[50:51]
	v_cvt_pk_bf16_f32 v48, v48, v49
	v_cvt_pk_bf16_f32 v49, v50, v51
	global_store_dwordx2 v[64:65], v[48:49], off offset:1536 nt
	s_branch .LBB0_904
